# v10 + first K iteration peeled: first MFMA of each accumulator takes C=0, per-unit accumulator zeroing deleted
# baseline (speedup 1.0000x reference)
; #define PG8_STAGE(bufoff, gbase, voff) do { _Pragma("unroll") for (int _i = 0; _i < 2; ++_i) \
;         __builtin_amdgcn_global_load_lds((const unsigned*)((const char*)(gbase) + (voff)[_i]), (PG8_LAS unsigned*)(lds + (bufoff) + ldsw + _i * 8192), 16, 0, 0); } while (0)
; #define PG8_LDA(dst, b, h) do { _Pragma("unroll") for (int m = 0; m < 4; ++m) _Pragma("unroll") for (int k = 0; k < 2; ++k) dst[m][k] = *(const PG8_LAS bf16x8*)(lds + PG8_SA(b, h) + aoff + m * 2048 + k * 1024); } while (0)
; #define PG8_WAIT_V(n) asm volatile("s_waitcnt vmcnt(" #n ")" ::: "memory")
; #define PG8_WAIT_L(n) asm volatile("s_waitcnt lgkmcnt(" #n ")" ::: "memory")
; #define PG8_BAR __builtin_amdgcn_s_barrier()
; template <class Epi, class Sched, bool ALIGN_EPI = false, bool SP2 = false>
; __device__ __forceinline__ void gemm_phase(PG8_LAS unsigned char* lds, const Gemm g, const Sched& S, const Epi& E) {
;     ...
;         const bool has_next = S.next(ui + 1, nxt);
;         const char* nA = has_next ? (const char*)g.A + (size_t)nxt.pm * tA + (size_t)nxt.pn * pnA : cA; const char* nB = has_next ? (const char*)g.Bt + (size_t)nxt.pn * tB : cB;
; #pragma nounroll
;         for (int t = 0; t < nt; t += 2) {
;             const bool last = (t == nt - 2);
;             const char* a1 = cA + (size_t)(t + 1) * kstep;
;             const char* a2 = last ? nA : cA + (size_t)(t + 2) * kstep; const char* b2 = last ? nB : cB + (size_t)(t + 2) * kstep;
;             const char* a3 = a2 + kstep; const char* b3 = b2 + kstep;
;             if (last && has_next) S.a_ready(nxt);
;             if constexpr (SP2) {
;             PG8_LDB(B0, 0, 0); PG8_LDB(B1, 0, 1); PG8_SCHED; PG8_LDA(At, 0, 0); PG8_STAGE(PG8_SA(1, 1), a1 + hA, voffA);
;             PG8_WAIT_V(8); PG8_WAIT_L(0); PG8_BAR; PG8_MMA(0, 0, At, B0); PG8_MMA(0, 1, At, B1); PG8_BAR; PG8_SCHED;
;             PG8_LDA(At, 0, 1); PG8_STAGE(PG8_SB(0, 0), b2, voffB); PG8_STAGE(PG8_SB(0, 1), b2 + hB, voffB); PG8_STAGE(PG8_SA(0, 0), a2, voffA);
;             PG8_WAIT_V(8); PG8_WAIT_L(0); PG8_BAR; PG8_MMA(1, 0, At, B0); PG8_MMA(1, 1, At, B1); PG8_BAR; PG8_SCHED;
;     ...
; #pragma unroll
;         for (int a = 0; a < 2; ++a)
; #pragma unroll
;             for (int b = 0; b < 2; ++b)
; #pragma unroll
;                 for (int m = 0; m < 4; ++m)
; #pragma unroll
;                     for (int n = 0; n < 2; ++n) acc[a][b][m][n] = (f32x4){0.f, 0.f, 0.f, 0.f};
.LBB0_189:
	s_ashr_i32 s55, s54, 31
	s_lshl_b64 s[56:57], s[54:55], 20
	s_add_u32 s56, s69, s56
	s_addc_u32 s57, s70, s57
	s_and_b64 s[58:59], s[8:9], exec
	s_cselect_b32 s11, s57, s63
	s_cselect_b32 s33, s56, s62
	s_ashr_i32 s53, s52, 31
	s_lshl_b64 s[58:59], s[52:53], 20
	s_add_u32 s58, s71, s58
	s_addc_u32 s59, s72, s59
	s_and_b64 s[66:67], s[8:9], exec
	s_cselect_b32 s53, s59, s65
	s_cselect_b32 s55, s58, s64
	s_add_u32 s62, s62, 0x80080
	s_addc_u32 s63, s63, 0
	s_add_u32 s61, s64, 0x100
	v_mov_b32_e32 v2, 0
	s_addc_u32 s96, s65, 0
	s_mov_b32 s97, -2
	v_mov_b32_e32 v3, v2
	ds_read_b128 v[130:133], v229
	ds_read_b128 v[134:137], v229 offset:1024
	ds_read_b128 v[138:141], v229 offset:2048
	ds_read_b128 v[142:145], v229 offset:3072
	ds_read_b128 v[146:149], v230
	ds_read_b128 v[150:153], v230 offset:1024
	ds_read_b128 v[154:157], v230 offset:2048
	ds_read_b128 v[158:161], v230 offset:3072
	s_add_u32 s64, s62, 0xfff80080
	s_addc_u32 s65, s63, -1
	s_cmp_eq_u32 s97, 28
	s_cselect_b32 s67, s11, s65
	s_cselect_b32 s66, s33, s64
	s_cselect_b32 s65, s53, s96
	s_cselect_b32 s64, s55, s61
	s_add_i32 m0, s74, 0xc000
	ds_read_b128 v[162:165], v231
	ds_read_b128 v[166:169], v231 offset:1024
	ds_read_b128 v[170:173], v231 offset:2048
	ds_read_b128 v[174:177], v231 offset:3072
	ds_read_b128 v[178:181], v231 offset:4096
	ds_read_b128 v[182:185], v231 offset:5120
	ds_read_b128 v[186:189], v231 offset:6144
	ds_read_b128 v[190:193], v231 offset:7168
	global_load_lds_dwordx4 v212, s[62:63]
	s_add_i32 m0, s74, 0xe000
	s_nop 0
	global_load_lds_dwordx4 v214, s[62:63]
	s_waitcnt vmcnt(8)
	s_waitcnt lgkmcnt(0)
	s_barrier
	s_waitcnt lgkmcnt(0)
	v_mfma_f32_16x16x32_bf16 v[126:129], v[130:133], v[162:165], 0
	v_mfma_f32_16x16x32_bf16 v[122:125], v[138:141], v[162:165], 0
	v_mfma_f32_16x16x32_bf16 v[110:113], v[130:133], v[170:173], 0
	v_mfma_f32_16x16x32_bf16 v[106:109], v[138:141], v[170:173], 0
	v_mfma_f32_16x16x32_bf16 v[94:97], v[130:133], v[178:181], 0
	v_mfma_f32_16x16x32_bf16 v[90:93], v[138:141], v[178:181], 0
	v_mfma_f32_16x16x32_bf16 v[78:81], v[130:133], v[186:189], 0
	v_mfma_f32_16x16x32_bf16 v[74:77], v[138:141], v[186:189], 0
	v_mfma_f32_16x16x32_bf16 v[126:129], v[134:137], v[166:169], v[126:129]
	v_mfma_f32_16x16x32_bf16 v[122:125], v[142:145], v[166:169], v[122:125]
	v_mfma_f32_16x16x32_bf16 v[110:113], v[134:137], v[174:177], v[110:113]
	v_mfma_f32_16x16x32_bf16 v[106:109], v[142:145], v[174:177], v[106:109]
	v_mfma_f32_16x16x32_bf16 v[94:97], v[134:137], v[182:185], v[94:97]
	v_mfma_f32_16x16x32_bf16 v[90:93], v[142:145], v[182:185], v[90:93]
	v_mfma_f32_16x16x32_bf16 v[78:81], v[134:137], v[190:193], v[78:81]
	v_mfma_f32_16x16x32_bf16 v[74:77], v[142:145], v[190:193], v[74:77]
	v_mfma_f32_16x16x32_bf16 v[118:121], v[146:149], v[162:165], 0
	v_mfma_f32_16x16x32_bf16 v[114:117], v[154:157], v[162:165], 0
	v_mfma_f32_16x16x32_bf16 v[102:105], v[146:149], v[170:173], 0
	v_mfma_f32_16x16x32_bf16 v[98:101], v[154:157], v[170:173], 0
	v_mfma_f32_16x16x32_bf16 v[86:89], v[146:149], v[178:181], 0
	v_mfma_f32_16x16x32_bf16 v[82:85], v[154:157], v[178:181], 0
	v_mfma_f32_16x16x32_bf16 v[70:73], v[146:149], v[186:189], 0
	v_mfma_f32_16x16x32_bf16 v[66:69], v[154:157], v[186:189], 0
	v_mfma_f32_16x16x32_bf16 v[118:121], v[150:153], v[166:169], v[118:121]
	v_mfma_f32_16x16x32_bf16 v[114:117], v[158:161], v[166:169], v[114:117]
	v_mfma_f32_16x16x32_bf16 v[102:105], v[150:153], v[174:177], v[102:105]
	v_mfma_f32_16x16x32_bf16 v[98:101], v[158:161], v[174:177], v[98:101]
	v_mfma_f32_16x16x32_bf16 v[86:89], v[150:153], v[182:185], v[86:89]
	v_mfma_f32_16x16x32_bf16 v[82:85], v[158:161], v[182:185], v[82:85]
	v_mfma_f32_16x16x32_bf16 v[70:73], v[150:153], v[190:193], v[70:73]
	v_mfma_f32_16x16x32_bf16 v[66:69], v[158:161], v[190:193], v[66:69]
	s_barrier
	s_add_i32 vcc_lo, s84, s73
	s_add_u32 s34, s64, s38
	s_addc_u32 s35, s65, s39
	s_mov_b32 m0, vcc_lo
	ds_read_b128 v[162:165], v231 offset:16384
	ds_read_b128 v[166:169], v231 offset:17408
	ds_read_b128 v[170:173], v231 offset:18432
	ds_read_b128 v[174:177], v231 offset:19456
	ds_read_b128 v[178:181], v231 offset:20480
	ds_read_b128 v[182:185], v231 offset:21504
	ds_read_b128 v[186:189], v231 offset:22528
	ds_read_b128 v[190:193], v231 offset:23552
	global_load_lds_dwordx4 v196, s[64:65]
	s_add_i32 m0, vcc_lo, 0x2000
	s_add_u32 vcc_lo, s64, 0x80000
	s_addc_u32 vcc_hi, s65, 0
	s_add_i32 s86, s85, s73
	global_load_lds_dwordx4 v200, s[64:65]
	s_mov_b32 m0, s86
	s_nop 0
	global_load_lds_dwordx4 v196, vcc
	s_add_i32 m0, s86, 0x2000
	s_nop 0
	global_load_lds_dwordx4 v200, vcc
	s_add_u32 s98, s66, s38
	s_addc_u32 s99, s67, s39
	s_mov_b32 m0, s74
	s_nop 0
	global_load_lds_dwordx4 v194, s[66:67]
	s_mov_b32 m0, s75
	s_nop 0
	global_load_lds_dwordx4 v198, s[66:67]
	s_waitcnt vmcnt(8)
	s_waitcnt lgkmcnt(0)
	s_barrier
; #define PG8_STAGE(bufoff, gbase, voff) do { _Pragma("unroll") for (int _i = 0; _i < 2; ++_i) \
;         __builtin_amdgcn_global_load_lds((const unsigned*)((const char*)(gbase) + (voff)[_i]), (PG8_LAS unsigned*)(lds + (bufoff) + ldsw + _i * 8192), 16, 0, 0); } while (0)
; #define PG8_LDA(dst, b, h) do { _Pragma("unroll") for (int m = 0; m < 4; ++m) _Pragma("unroll") for (int k = 0; k < 2; ++k) dst[m][k] = *(const PG8_LAS bf16x8*)(lds + PG8_SA(b, h) + aoff + m * 2048 + k * 1024); } while (0)
; #define PG8_LDB(dst, b, h) do { _Pragma("unroll") for (int n = 0; n < 2; ++n) _Pragma("unroll") for (int k = 0; k < 2; ++k) dst[n][k] = *(const PG8_LAS bf16x8*)(lds + PG8_SB(b, h) + boff + n * 2048 + k * 1024); } while (0)
; #define PG8_MMA(ai, bj, At, Bt) do { __builtin_amdgcn_s_setprio(1); _Pragma("unroll") for (int m = 0; m < 4; ++m) _Pragma("unroll") for (int n = 0; n < 2; ++n) _Pragma("unroll") for (int k = 0; k < 2; ++k) \
;         acc[ai][bj][m][n] = __builtin_amdgcn_mfma_f32_16x16x32_bf16(Bt[n][k], At[m][k], acc[ai][bj][m][n], 0, 0, 0); __builtin_amdgcn_s_setprio(0); } while (0)
; #define PG8_WAIT_V(n) asm volatile("s_waitcnt vmcnt(" #n ")" ::: "memory")
; #define PG8_WAIT_L(n) asm volatile("s_waitcnt lgkmcnt(" #n ")" ::: "memory")
; #define PG8_BAR __builtin_amdgcn_s_barrier()
; #define PG8_SCHED __builtin_amdgcn_sched_barrier(0)
; template <class Epi, class Sched, bool ALIGN_EPI = false, bool SP2 = false>
; __device__ __forceinline__ void gemm_phase(PG8_LAS unsigned char* lds, const Gemm g, const Sched& S, const Epi& E) {
;     ...
;             PG8_WAIT_V(8); PG8_WAIT_L(0); PG8_BAR; PG8_MMA(0, 0, At, B0); PG8_MMA(0, 1, At, B1); PG8_BAR; PG8_SCHED;
;             PG8_LDA(At, 0, 1); PG8_STAGE(PG8_SB(0, 0), b2, voffB); PG8_STAGE(PG8_SB(0, 1), b2 + hB, voffB); PG8_STAGE(PG8_SA(0, 0), a2, voffA);
;             PG8_WAIT_V(8); PG8_WAIT_L(0); PG8_BAR; PG8_MMA(1, 0, At, B0); PG8_MMA(1, 1, At, B1); PG8_BAR; PG8_SCHED;
;             PG8_LDB(B0, 1, 0); PG8_LDB(B1, 1, 1); PG8_SCHED; PG8_LDA(At, 1, 0); PG8_STAGE(PG8_SA(0, 1), a2 + hA, voffA);
;             PG8_WAIT_V(8); PG8_WAIT_L(0); PG8_BAR; PG8_MMA(0, 0, At, B0); PG8_MMA(0, 1, At, B1); PG8_BAR; PG8_SCHED;
	s_waitcnt lgkmcnt(0)
	v_mfma_f32_16x16x32_bf16 v[62:65], v[130:133], v[162:165], 0
	v_mfma_f32_16x16x32_bf16 v[58:61], v[138:141], v[162:165], 0
	v_mfma_f32_16x16x32_bf16 v[46:49], v[130:133], v[170:173], 0
	v_mfma_f32_16x16x32_bf16 v[42:45], v[138:141], v[170:173], 0
	v_mfma_f32_16x16x32_bf16 v[30:33], v[130:133], v[178:181], 0
	v_mfma_f32_16x16x32_bf16 v[26:29], v[138:141], v[178:181], 0
	v_mfma_f32_16x16x32_bf16 v[14:17], v[130:133], v[186:189], 0
	v_mfma_f32_16x16x32_bf16 v[10:13], v[138:141], v[186:189], 0
	v_mfma_f32_16x16x32_bf16 v[62:65], v[134:137], v[166:169], v[62:65]
	v_mfma_f32_16x16x32_bf16 v[58:61], v[142:145], v[166:169], v[58:61]
	v_mfma_f32_16x16x32_bf16 v[46:49], v[134:137], v[174:177], v[46:49]
	v_mfma_f32_16x16x32_bf16 v[42:45], v[142:145], v[174:177], v[42:45]
	v_mfma_f32_16x16x32_bf16 v[30:33], v[134:137], v[182:185], v[30:33]
	v_mfma_f32_16x16x32_bf16 v[26:29], v[142:145], v[182:185], v[26:29]
	v_mfma_f32_16x16x32_bf16 v[14:17], v[134:137], v[190:193], v[14:17]
	v_mfma_f32_16x16x32_bf16 v[10:13], v[142:145], v[190:193], v[10:13]
	v_mfma_f32_16x16x32_bf16 v[54:57], v[146:149], v[162:165], 0
	v_mfma_f32_16x16x32_bf16 v[50:53], v[154:157], v[162:165], 0
	v_mfma_f32_16x16x32_bf16 v[38:41], v[146:149], v[170:173], 0
	v_mfma_f32_16x16x32_bf16 v[34:37], v[154:157], v[170:173], 0
	v_mfma_f32_16x16x32_bf16 v[22:25], v[146:149], v[178:181], 0
	v_mfma_f32_16x16x32_bf16 v[18:21], v[154:157], v[178:181], 0
	v_mfma_f32_16x16x32_bf16 v[6:9], v[146:149], v[186:189], 0
	v_mfma_f32_16x16x32_bf16 v[2:5], v[154:157], v[186:189], 0
	v_mfma_f32_16x16x32_bf16 v[54:57], v[150:153], v[166:169], v[54:57]
	v_mfma_f32_16x16x32_bf16 v[50:53], v[158:161], v[166:169], v[50:53]
	v_mfma_f32_16x16x32_bf16 v[38:41], v[150:153], v[174:177], v[38:41]
	v_mfma_f32_16x16x32_bf16 v[34:37], v[158:161], v[174:177], v[34:37]
	v_mfma_f32_16x16x32_bf16 v[22:25], v[150:153], v[182:185], v[22:25]
	v_mfma_f32_16x16x32_bf16 v[18:21], v[158:161], v[182:185], v[18:21]
	v_mfma_f32_16x16x32_bf16 v[6:9], v[150:153], v[190:193], v[6:9]
	v_mfma_f32_16x16x32_bf16 v[2:5], v[158:161], v[190:193], v[2:5]
	s_barrier
	s_add_i32 s86, 0, 0x18000
	s_add_i32 vcc_lo, 0, 0x1c000
	v_add_u32_e32 v142, s86, v223
	v_add_u32_e32 v158, vcc_lo, v223
	ds_read_b128 v[130:133], v142
	ds_read_b128 v[134:137], v142 offset:1024
	ds_read_b128 v[138:141], v142 offset:2048
	ds_read_b128 v[142:145], v142 offset:3072
	ds_read_b128 v[146:149], v158
	ds_read_b128 v[150:153], v158 offset:1024
	ds_read_b128 v[154:157], v158 offset:2048
	ds_read_b128 v[158:161], v158 offset:3072
	s_add_u32 s66, s66, 0x80000
	s_addc_u32 s67, s67, 0
	s_mov_b32 m0, s76
	ds_read_b128 v[162:165], v231 offset:32768
	ds_read_b128 v[166:169], v231 offset:33792
	ds_read_b128 v[170:173], v231 offset:34816
	ds_read_b128 v[174:177], v231 offset:35840
	ds_read_b128 v[178:181], v231 offset:36864
	ds_read_b128 v[182:185], v231 offset:37888
	ds_read_b128 v[186:189], v231 offset:38912
	ds_read_b128 v[190:193], v231 offset:39936
	global_load_lds_dwordx4 v194, s[66:67]
	s_mov_b32 m0, s77
	s_nop 0
	global_load_lds_dwordx4 v198, s[66:67]
	s_waitcnt vmcnt(8)
	s_waitcnt lgkmcnt(0)
	s_barrier
	s_waitcnt lgkmcnt(0)
	v_mfma_f32_16x16x32_bf16 v[126:129], v[130:133], v[162:165], v[126:129]
	v_mfma_f32_16x16x32_bf16 v[122:125], v[138:141], v[162:165], v[122:125]
	v_mfma_f32_16x16x32_bf16 v[110:113], v[130:133], v[170:173], v[110:113]
	v_mfma_f32_16x16x32_bf16 v[106:109], v[138:141], v[170:173], v[106:109]
	v_mfma_f32_16x16x32_bf16 v[94:97], v[130:133], v[178:181], v[94:97]
	v_mfma_f32_16x16x32_bf16 v[90:93], v[138:141], v[178:181], v[90:93]
	v_mfma_f32_16x16x32_bf16 v[78:81], v[130:133], v[186:189], v[78:81]
	v_mfma_f32_16x16x32_bf16 v[74:77], v[138:141], v[186:189], v[74:77]
	v_mfma_f32_16x16x32_bf16 v[126:129], v[134:137], v[166:169], v[126:129]
	v_mfma_f32_16x16x32_bf16 v[122:125], v[142:145], v[166:169], v[122:125]
	v_mfma_f32_16x16x32_bf16 v[110:113], v[134:137], v[174:177], v[110:113]
	v_mfma_f32_16x16x32_bf16 v[106:109], v[142:145], v[174:177], v[106:109]
	v_mfma_f32_16x16x32_bf16 v[94:97], v[134:137], v[182:185], v[94:97]
	v_mfma_f32_16x16x32_bf16 v[90:93], v[142:145], v[182:185], v[90:93]
	v_mfma_f32_16x16x32_bf16 v[78:81], v[134:137], v[190:193], v[78:81]
	v_mfma_f32_16x16x32_bf16 v[74:77], v[142:145], v[190:193], v[74:77]
	v_mfma_f32_16x16x32_bf16 v[118:121], v[146:149], v[162:165], v[118:121]
	v_mfma_f32_16x16x32_bf16 v[114:117], v[154:157], v[162:165], v[114:117]
	v_mfma_f32_16x16x32_bf16 v[102:105], v[146:149], v[170:173], v[102:105]
	v_mfma_f32_16x16x32_bf16 v[98:101], v[154:157], v[170:173], v[98:101]
	v_mfma_f32_16x16x32_bf16 v[86:89], v[146:149], v[178:181], v[86:89]
	v_mfma_f32_16x16x32_bf16 v[82:85], v[154:157], v[178:181], v[82:85]
	v_mfma_f32_16x16x32_bf16 v[70:73], v[146:149], v[186:189], v[70:73]
	v_mfma_f32_16x16x32_bf16 v[66:69], v[154:157], v[186:189], v[66:69]
	v_mfma_f32_16x16x32_bf16 v[118:121], v[150:153], v[166:169], v[118:121]
	v_mfma_f32_16x16x32_bf16 v[114:117], v[158:161], v[166:169], v[114:117]
	v_mfma_f32_16x16x32_bf16 v[102:105], v[150:153], v[174:177], v[102:105]
	v_mfma_f32_16x16x32_bf16 v[98:101], v[158:161], v[174:177], v[98:101]
	v_mfma_f32_16x16x32_bf16 v[86:89], v[150:153], v[182:185], v[86:89]
	v_mfma_f32_16x16x32_bf16 v[82:85], v[158:161], v[182:185], v[82:85]
	v_mfma_f32_16x16x32_bf16 v[70:73], v[150:153], v[190:193], v[70:73]
	v_mfma_f32_16x16x32_bf16 v[66:69], v[158:161], v[190:193], v[66:69]
	s_barrier
; #define PG8_STAGE(bufoff, gbase, voff) do { _Pragma("unroll") for (int _i = 0; _i < 2; ++_i) \
;         __builtin_amdgcn_global_load_lds((const unsigned*)((const char*)(gbase) + (voff)[_i]), (PG8_LAS unsigned*)(lds + (bufoff) + ldsw + _i * 8192), 16, 0, 0); } while (0)
; #define PG8_LDA(dst, b, h) do { _Pragma("unroll") for (int m = 0; m < 4; ++m) _Pragma("unroll") for (int k = 0; k < 2; ++k) dst[m][k] = *(const PG8_LAS bf16x8*)(lds + PG8_SA(b, h) + aoff + m * 2048 + k * 1024); } while (0)
; #define PG8_MMA(ai, bj, At, Bt) do { __builtin_amdgcn_s_setprio(1); _Pragma("unroll") for (int m = 0; m < 4; ++m) _Pragma("unroll") for (int n = 0; n < 2; ++n) _Pragma("unroll") for (int k = 0; k < 2; ++k) \
;         acc[ai][bj][m][n] = __builtin_amdgcn_mfma_f32_16x16x32_bf16(Bt[n][k], At[m][k], acc[ai][bj][m][n], 0, 0, 0); __builtin_amdgcn_s_setprio(0); } while (0)
; #define PG8_WAIT_V(n) asm volatile("s_waitcnt vmcnt(" #n ")" ::: "memory")
; #define PG8_WAIT_L(n) asm volatile("s_waitcnt lgkmcnt(" #n ")" ::: "memory")
; #define PG8_BAR __builtin_amdgcn_s_barrier()
; #define PG8_SCHED __builtin_amdgcn_sched_barrier(0)
; template <class Epi, class Sched, bool ALIGN_EPI = false, bool SP2 = false>
; __device__ __forceinline__ void gemm_phase(PG8_LAS unsigned char* lds, const Gemm g, const Sched& S, const Epi& E) {
;     ...
;         for (int t = 0; t < nt; t += 2) {
;             const bool last = (t == nt - 2);
;             const char* a1 = cA + (size_t)(t + 1) * kstep;
;             const char* a2 = last ? nA : cA + (size_t)(t + 2) * kstep; const char* b2 = last ? nB : cB + (size_t)(t + 2) * kstep;
;     ...
;             PG8_LDA(At, 1, 1); PG8_STAGE(PG8_SB(1, 0), b3, voffB); PG8_STAGE(PG8_SB(1, 1), b3 + hB, voffB); PG8_STAGE(PG8_SA(1, 0), a3, voffA);
;             PG8_WAIT_V(8); PG8_WAIT_L(0); PG8_BAR; PG8_MMA(1, 0, At, B0); PG8_MMA(1, 1, At, B1); PG8_BAR; PG8_SCHED;
	s_add_i32 s66, s86, s73
	s_mov_b32 m0, s66
	ds_read_b128 v[162:165], v231 offset:49152
	ds_read_b128 v[166:169], v231 offset:50176
	ds_read_b128 v[170:173], v231 offset:51200
	ds_read_b128 v[174:177], v231 offset:52224
	ds_read_b128 v[178:181], v231 offset:53248
	ds_read_b128 v[182:185], v231 offset:54272
	ds_read_b128 v[186:189], v231 offset:55296
	ds_read_b128 v[190:193], v231 offset:56320
	global_load_lds_dwordx4 v196, s[34:35]
	s_add_i32 m0, s66, 0x2000
	s_add_u32 s64, s64, 0x80080
	s_addc_u32 s65, s65, 0
	s_add_i32 s66, vcc_lo, s73
	global_load_lds_dwordx4 v200, s[34:35]
	s_mov_b32 m0, s66
	s_nop 0
	global_load_lds_dwordx4 v196, s[64:65]
	s_add_i32 m0, s66, 0x2000
	s_nop 0
	global_load_lds_dwordx4 v200, s[64:65]
	s_mov_b32 m0, s81
	s_nop 0
	global_load_lds_dwordx4 v194, s[98:99]
	s_mov_b32 m0, s82
	s_nop 0
	global_load_lds_dwordx4 v198, s[98:99]
	s_waitcnt vmcnt(8)
	s_waitcnt lgkmcnt(0)
	s_barrier
	s_waitcnt lgkmcnt(0)
	v_mfma_f32_16x16x32_bf16 v[62:65], v[130:133], v[162:165], v[62:65]
	v_mfma_f32_16x16x32_bf16 v[58:61], v[138:141], v[162:165], v[58:61]
	v_mfma_f32_16x16x32_bf16 v[46:49], v[130:133], v[170:173], v[46:49]
	v_mfma_f32_16x16x32_bf16 v[42:45], v[138:141], v[170:173], v[42:45]
	v_mfma_f32_16x16x32_bf16 v[30:33], v[130:133], v[178:181], v[30:33]
	v_mfma_f32_16x16x32_bf16 v[26:29], v[138:141], v[178:181], v[26:29]
	v_mfma_f32_16x16x32_bf16 v[14:17], v[130:133], v[186:189], v[14:17]
	v_mfma_f32_16x16x32_bf16 v[10:13], v[138:141], v[186:189], v[10:13]
	v_mfma_f32_16x16x32_bf16 v[62:65], v[134:137], v[166:169], v[62:65]
	v_mfma_f32_16x16x32_bf16 v[58:61], v[142:145], v[166:169], v[58:61]
	v_mfma_f32_16x16x32_bf16 v[46:49], v[134:137], v[174:177], v[46:49]
	v_mfma_f32_16x16x32_bf16 v[42:45], v[142:145], v[174:177], v[42:45]
	v_mfma_f32_16x16x32_bf16 v[30:33], v[134:137], v[182:185], v[30:33]
	v_mfma_f32_16x16x32_bf16 v[26:29], v[142:145], v[182:185], v[26:29]
	v_mfma_f32_16x16x32_bf16 v[14:17], v[134:137], v[190:193], v[14:17]
	v_mfma_f32_16x16x32_bf16 v[10:13], v[142:145], v[190:193], v[10:13]
	v_mfma_f32_16x16x32_bf16 v[54:57], v[146:149], v[162:165], v[54:57]
	v_mfma_f32_16x16x32_bf16 v[50:53], v[154:157], v[162:165], v[50:53]
	v_mfma_f32_16x16x32_bf16 v[38:41], v[146:149], v[170:173], v[38:41]
	v_mfma_f32_16x16x32_bf16 v[34:37], v[154:157], v[170:173], v[34:37]
	v_mfma_f32_16x16x32_bf16 v[22:25], v[146:149], v[178:181], v[22:25]
	v_mfma_f32_16x16x32_bf16 v[18:21], v[154:157], v[178:181], v[18:21]
	v_mfma_f32_16x16x32_bf16 v[6:9], v[146:149], v[186:189], v[6:9]
	v_mfma_f32_16x16x32_bf16 v[2:5], v[154:157], v[186:189], v[2:5]
	v_mfma_f32_16x16x32_bf16 v[54:57], v[150:153], v[166:169], v[54:57]
	v_mfma_f32_16x16x32_bf16 v[50:53], v[158:161], v[166:169], v[50:53]
	v_mfma_f32_16x16x32_bf16 v[38:41], v[150:153], v[174:177], v[38:41]
	v_mfma_f32_16x16x32_bf16 v[34:37], v[158:161], v[174:177], v[34:37]
	v_mfma_f32_16x16x32_bf16 v[22:25], v[150:153], v[182:185], v[22:25]
	v_mfma_f32_16x16x32_bf16 v[18:21], v[158:161], v[182:185], v[18:21]
	v_mfma_f32_16x16x32_bf16 v[6:9], v[150:153], v[190:193], v[6:9]
	v_mfma_f32_16x16x32_bf16 v[2:5], v[158:161], v[190:193], v[2:5]
	s_barrier
	s_add_i32 s97, s97, 2
	s_add_u32 s62, s62, 0x100
	s_addc_u32 s63, s63, 0
	s_add_u32 s61, s61, 0x100
	s_addc_u32 s96, s96, 0
	s_cmp_gt_u32 s97, 29

; #define PG8_STAGE(bufoff, gbase, voff) do { _Pragma("unroll") for (int _i = 0; _i < 2; ++_i) \
;         __builtin_amdgcn_global_load_lds((const unsigned*)((const char*)(gbase) + (voff)[_i]), (PG8_LAS unsigned*)(lds + (bufoff) + ldsw + _i * 8192), 16, 0, 0); } while (0)
; #define PG8_LDA(dst, b, h) do { _Pragma("unroll") for (int m = 0; m < 4; ++m) _Pragma("unroll") for (int k = 0; k < 2; ++k) dst[m][k] = *(const PG8_LAS bf16x8*)(lds + PG8_SA(b, h) + aoff + m * 2048 + k * 1024); } while (0)
; #define PG8_WAIT_V(n) asm volatile("s_waitcnt vmcnt(" #n ")" ::: "memory")
; #define PG8_WAIT_L(n) asm volatile("s_waitcnt lgkmcnt(" #n ")" ::: "memory")
; #define PG8_BAR __builtin_amdgcn_s_barrier()
; template <class Epi, class Sched, bool ALIGN_EPI = false, bool SP2 = false>
; __device__ __forceinline__ void gemm_phase(PG8_LAS unsigned char* lds, const Gemm g, const Sched& S, const Epi& E) {
;     ...
;         const bool has_next = S.next(ui + 1, nxt);
;         const char* nA = has_next ? (const char*)g.A + (size_t)nxt.pm * tA + (size_t)nxt.pn * pnA : cA; const char* nB = has_next ? (const char*)g.Bt + (size_t)nxt.pn * tB : cB;
; #pragma nounroll
;         for (int t = 0; t < nt; t += 2) {
;             const bool last = (t == nt - 2);
;             const char* a1 = cA + (size_t)(t + 1) * kstep;
;             const char* a2 = last ? nA : cA + (size_t)(t + 2) * kstep; const char* b2 = last ? nB : cB + (size_t)(t + 2) * kstep;
;             const char* a3 = a2 + kstep; const char* b3 = b2 + kstep;
;             if (last && has_next) S.a_ready(nxt);
;             if constexpr (SP2) {
;             PG8_LDB(B0, 0, 0); PG8_LDB(B1, 0, 1); PG8_SCHED; PG8_LDA(At, 0, 0); PG8_STAGE(PG8_SA(1, 1), a1 + hA, voffA);
;             PG8_WAIT_V(8); PG8_WAIT_L(0); PG8_BAR; PG8_MMA(0, 0, At, B0); PG8_MMA(0, 1, At, B1); PG8_BAR; PG8_SCHED;
;             PG8_LDA(At, 0, 1); PG8_STAGE(PG8_SB(0, 0), b2, voffB); PG8_STAGE(PG8_SB(0, 1), b2 + hB, voffB); PG8_STAGE(PG8_SA(0, 0), a2, voffA);
;             PG8_WAIT_V(8); PG8_WAIT_L(0); PG8_BAR; PG8_MMA(1, 0, At, B0); PG8_MMA(1, 1, At, B1); PG8_BAR; PG8_SCHED;
;     ...
; #pragma unroll
;         for (int a = 0; a < 2; ++a)
; #pragma unroll
;             for (int b = 0; b < 2; ++b)
; #pragma unroll
;                 for (int m = 0; m < 4; ++m)
; #pragma unroll
;                     for (int n = 0; n < 2; ++n) acc[a][b][m][n] = (f32x4){0.f, 0.f, 0.f, 0.f};
.LBB0_867:
	s_ashr_i32 s23, s22, 31
	s_lshl_b64 s[24:25], s[22:23], 19
	s_add_u32 s24, s33, s24
	s_addc_u32 s25, s48, s25
	s_and_b64 s[38:39], s[4:5], exec
	s_cselect_b32 s23, s25, s43
	s_cselect_b32 s67, s24, s42
	s_ashr_i32 s21, s20, 31
	s_lshl_b64 s[38:39], s[20:21], 19
	s_add_u32 s38, s49, s38
	s_addc_u32 s39, s51, s39
	s_and_b64 s[46:47], s[4:5], exec
	s_cselect_b32 s21, s39, s45
	s_cselect_b32 s69, s38, s44
	s_add_u32 s42, s42, 0x40080
	s_addc_u32 s43, s43, 0
	s_add_u32 s70, s44, 0x100
	v_mov_b32_e32 v2, 0
	s_addc_u32 s71, s45, 0
	s_mov_b32 s72, -2
	v_mov_b32_e32 v3, v2
	ds_read_b128 v[146:149], v156
	ds_read_b128 v[150:153], v156 offset:1024
	ds_read_b128 v[160:163], v156 offset:2048
	ds_read_b128 v[164:167], v156 offset:3072
	ds_read_b128 v[168:171], v157
	ds_read_b128 v[172:175], v157 offset:1024
	ds_read_b128 v[176:179], v157 offset:2048
	ds_read_b128 v[180:183], v157 offset:3072
	s_add_u32 s18, s42, 0xfffc0080
	s_addc_u32 s19, s43, -1
	s_cmp_eq_u32 s72, 12
	s_cselect_b32 s47, s23, s19
	s_cselect_b32 s46, s67, s18
	s_cselect_b32 s45, s21, s71
	s_cselect_b32 s44, s69, s70
	s_add_i32 m0, s41, 0xc000
	ds_read_b128 v[184:187], v158
	ds_read_b128 v[188:191], v158 offset:1024
	ds_read_b128 v[192:195], v158 offset:2048
	ds_read_b128 v[196:199], v158 offset:3072
	ds_read_b128 v[200:203], v158 offset:4096
	ds_read_b128 v[204:207], v158 offset:5120
	ds_read_b128 v[208:211], v158 offset:6144
	ds_read_b128 v[212:215], v158 offset:7168
	global_load_lds_dwordx4 v138, s[42:43]
	s_add_i32 m0, s41, 0xe000
	s_nop 0
	global_load_lds_dwordx4 v140, s[42:43]
	s_waitcnt vmcnt(8)
	s_waitcnt lgkmcnt(0)
	s_barrier
	s_waitcnt lgkmcnt(0)
	v_mfma_f32_16x16x32_bf16 v[126:129], v[146:149], v[184:187], 0
	v_mfma_f32_16x16x32_bf16 v[122:125], v[160:163], v[184:187], 0
	v_mfma_f32_16x16x32_bf16 v[114:117], v[146:149], v[192:195], 0
	v_mfma_f32_16x16x32_bf16 v[106:109], v[160:163], v[192:195], 0
	v_mfma_f32_16x16x32_bf16 v[98:101], v[146:149], v[200:203], 0
	v_mfma_f32_16x16x32_bf16 v[90:93], v[160:163], v[200:203], 0
	v_mfma_f32_16x16x32_bf16 v[82:85], v[146:149], v[208:211], 0
	v_mfma_f32_16x16x32_bf16 v[74:77], v[160:163], v[208:211], 0
	v_mfma_f32_16x16x32_bf16 v[126:129], v[150:153], v[188:191], v[126:129]
	v_mfma_f32_16x16x32_bf16 v[122:125], v[164:167], v[188:191], v[122:125]
	v_mfma_f32_16x16x32_bf16 v[114:117], v[150:153], v[196:199], v[114:117]
	v_mfma_f32_16x16x32_bf16 v[106:109], v[164:167], v[196:199], v[106:109]
	v_mfma_f32_16x16x32_bf16 v[98:101], v[150:153], v[204:207], v[98:101]
	v_mfma_f32_16x16x32_bf16 v[90:93], v[164:167], v[204:207], v[90:93]
	v_mfma_f32_16x16x32_bf16 v[82:85], v[150:153], v[212:215], v[82:85]
	v_mfma_f32_16x16x32_bf16 v[74:77], v[164:167], v[212:215], v[74:77]
	v_mfma_f32_16x16x32_bf16 v[118:121], v[168:171], v[184:187], 0
	v_mfma_f32_16x16x32_bf16 v[110:113], v[176:179], v[184:187], 0
	v_mfma_f32_16x16x32_bf16 v[102:105], v[168:171], v[192:195], 0
	v_mfma_f32_16x16x32_bf16 v[94:97], v[176:179], v[192:195], 0
	v_mfma_f32_16x16x32_bf16 v[86:89], v[168:171], v[200:203], 0
	v_mfma_f32_16x16x32_bf16 v[78:81], v[176:179], v[200:203], 0
	v_mfma_f32_16x16x32_bf16 v[70:73], v[168:171], v[208:211], 0
	v_mfma_f32_16x16x32_bf16 v[66:69], v[176:179], v[208:211], 0
	v_mfma_f32_16x16x32_bf16 v[118:121], v[172:175], v[188:191], v[118:121]
	v_mfma_f32_16x16x32_bf16 v[110:113], v[180:183], v[188:191], v[110:113]
	v_mfma_f32_16x16x32_bf16 v[102:105], v[172:175], v[196:199], v[102:105]
	v_mfma_f32_16x16x32_bf16 v[94:97], v[180:183], v[196:199], v[94:97]
	v_mfma_f32_16x16x32_bf16 v[86:89], v[172:175], v[204:207], v[86:89]
	v_mfma_f32_16x16x32_bf16 v[78:81], v[180:183], v[204:207], v[78:81]
	v_mfma_f32_16x16x32_bf16 v[70:73], v[172:175], v[212:215], v[70:73]
	v_mfma_f32_16x16x32_bf16 v[66:69], v[180:183], v[212:215], v[66:69]
	s_barrier
	s_add_i32 s18, s64, s52
	s_add_u32 s78, s44, s8
	s_addc_u32 s79, s45, s9
	s_mov_b32 m0, s18
	ds_read_b128 v[184:187], v158 offset:16384
	ds_read_b128 v[188:191], v158 offset:17408
	ds_read_b128 v[192:195], v158 offset:18432
	ds_read_b128 v[196:199], v158 offset:19456
	ds_read_b128 v[200:203], v158 offset:20480
	ds_read_b128 v[204:207], v158 offset:21504
	ds_read_b128 v[208:211], v158 offset:22528
	ds_read_b128 v[212:215], v158 offset:23552
	global_load_lds_dwordx4 v134, s[44:45]
	s_add_i32 m0, s18, 0x2000
	s_add_u32 s74, s44, 0x40000
	s_addc_u32 s75, s45, 0
	s_add_i32 s18, s65, s52
	global_load_lds_dwordx4 v130, s[44:45]
	s_mov_b32 m0, s18
	s_nop 0
	global_load_lds_dwordx4 v134, s[74:75]
	s_add_i32 m0, s18, 0x2000
	s_nop 0
	global_load_lds_dwordx4 v130, s[74:75]
	s_add_u32 s80, s46, s8
	s_addc_u32 s81, s47, s9
	s_mov_b32 m0, s41
	s_nop 0
	global_load_lds_dwordx4 v136, s[46:47]
	s_mov_b32 m0, s53
	s_nop 0
	global_load_lds_dwordx4 v132, s[46:47]
	s_waitcnt vmcnt(8)
	s_waitcnt lgkmcnt(0)
	s_barrier
; #define PG8_STAGE(bufoff, gbase, voff) do { _Pragma("unroll") for (int _i = 0; _i < 2; ++_i) \
;         __builtin_amdgcn_global_load_lds((const unsigned*)((const char*)(gbase) + (voff)[_i]), (PG8_LAS unsigned*)(lds + (bufoff) + ldsw + _i * 8192), 16, 0, 0); } while (0)
; #define PG8_LDA(dst, b, h) do { _Pragma("unroll") for (int m = 0; m < 4; ++m) _Pragma("unroll") for (int k = 0; k < 2; ++k) dst[m][k] = *(const PG8_LAS bf16x8*)(lds + PG8_SA(b, h) + aoff + m * 2048 + k * 1024); } while (0)
; #define PG8_LDB(dst, b, h) do { _Pragma("unroll") for (int n = 0; n < 2; ++n) _Pragma("unroll") for (int k = 0; k < 2; ++k) dst[n][k] = *(const PG8_LAS bf16x8*)(lds + PG8_SB(b, h) + boff + n * 2048 + k * 1024); } while (0)
; #define PG8_MMA(ai, bj, At, Bt) do { __builtin_amdgcn_s_setprio(1); _Pragma("unroll") for (int m = 0; m < 4; ++m) _Pragma("unroll") for (int n = 0; n < 2; ++n) _Pragma("unroll") for (int k = 0; k < 2; ++k) \
;         acc[ai][bj][m][n] = __builtin_amdgcn_mfma_f32_16x16x32_bf16(Bt[n][k], At[m][k], acc[ai][bj][m][n], 0, 0, 0); __builtin_amdgcn_s_setprio(0); } while (0)
; #define PG8_WAIT_V(n) asm volatile("s_waitcnt vmcnt(" #n ")" ::: "memory")
; #define PG8_WAIT_L(n) asm volatile("s_waitcnt lgkmcnt(" #n ")" ::: "memory")
; #define PG8_BAR __builtin_amdgcn_s_barrier()
; #define PG8_SCHED __builtin_amdgcn_sched_barrier(0)
; template <class Epi, class Sched, bool ALIGN_EPI = false, bool SP2 = false>
; __device__ __forceinline__ void gemm_phase(PG8_LAS unsigned char* lds, const Gemm g, const Sched& S, const Epi& E) {
;     ...
;             PG8_WAIT_V(8); PG8_WAIT_L(0); PG8_BAR; PG8_MMA(0, 0, At, B0); PG8_MMA(0, 1, At, B1); PG8_BAR; PG8_SCHED;
;             PG8_LDA(At, 0, 1); PG8_STAGE(PG8_SB(0, 0), b2, voffB); PG8_STAGE(PG8_SB(0, 1), b2 + hB, voffB); PG8_STAGE(PG8_SA(0, 0), a2, voffA);
;             PG8_WAIT_V(8); PG8_WAIT_L(0); PG8_BAR; PG8_MMA(1, 0, At, B0); PG8_MMA(1, 1, At, B1); PG8_BAR; PG8_SCHED;
;             PG8_LDB(B0, 1, 0); PG8_LDB(B1, 1, 1); PG8_SCHED; PG8_LDA(At, 1, 0); PG8_STAGE(PG8_SA(0, 1), a2 + hA, voffA);
;             PG8_WAIT_V(8); PG8_WAIT_L(0); PG8_BAR; PG8_MMA(0, 0, At, B0); PG8_MMA(0, 1, At, B1); PG8_BAR; PG8_SCHED;
	s_waitcnt lgkmcnt(0)
	v_mfma_f32_16x16x32_bf16 v[62:65], v[146:149], v[184:187], 0
	v_mfma_f32_16x16x32_bf16 v[58:61], v[160:163], v[184:187], 0
	v_mfma_f32_16x16x32_bf16 v[50:53], v[146:149], v[192:195], 0
	v_mfma_f32_16x16x32_bf16 v[42:45], v[160:163], v[192:195], 0
	v_mfma_f32_16x16x32_bf16 v[34:37], v[146:149], v[200:203], 0
	v_mfma_f32_16x16x32_bf16 v[26:29], v[160:163], v[200:203], 0
	v_mfma_f32_16x16x32_bf16 v[18:21], v[146:149], v[208:211], 0
	v_mfma_f32_16x16x32_bf16 v[10:13], v[160:163], v[208:211], 0
	v_mfma_f32_16x16x32_bf16 v[62:65], v[150:153], v[188:191], v[62:65]
	v_mfma_f32_16x16x32_bf16 v[58:61], v[164:167], v[188:191], v[58:61]
	v_mfma_f32_16x16x32_bf16 v[50:53], v[150:153], v[196:199], v[50:53]
	v_mfma_f32_16x16x32_bf16 v[42:45], v[164:167], v[196:199], v[42:45]
	v_mfma_f32_16x16x32_bf16 v[34:37], v[150:153], v[204:207], v[34:37]
	v_mfma_f32_16x16x32_bf16 v[26:29], v[164:167], v[204:207], v[26:29]
	v_mfma_f32_16x16x32_bf16 v[18:21], v[150:153], v[212:215], v[18:21]
	v_mfma_f32_16x16x32_bf16 v[10:13], v[164:167], v[212:215], v[10:13]
	v_mfma_f32_16x16x32_bf16 v[54:57], v[168:171], v[184:187], 0
	v_mfma_f32_16x16x32_bf16 v[46:49], v[176:179], v[184:187], 0
	v_mfma_f32_16x16x32_bf16 v[38:41], v[168:171], v[192:195], 0
	v_mfma_f32_16x16x32_bf16 v[30:33], v[176:179], v[192:195], 0
	v_mfma_f32_16x16x32_bf16 v[22:25], v[168:171], v[200:203], 0
	v_mfma_f32_16x16x32_bf16 v[14:17], v[176:179], v[200:203], 0
	v_mfma_f32_16x16x32_bf16 v[6:9], v[168:171], v[208:211], 0
	v_mfma_f32_16x16x32_bf16 v[2:5], v[176:179], v[208:211], 0
	v_mfma_f32_16x16x32_bf16 v[54:57], v[172:175], v[188:191], v[54:57]
	v_mfma_f32_16x16x32_bf16 v[46:49], v[180:183], v[188:191], v[46:49]
	v_mfma_f32_16x16x32_bf16 v[38:41], v[172:175], v[196:199], v[38:41]
	v_mfma_f32_16x16x32_bf16 v[30:33], v[180:183], v[196:199], v[30:33]
	v_mfma_f32_16x16x32_bf16 v[22:25], v[172:175], v[204:207], v[22:25]
	v_mfma_f32_16x16x32_bf16 v[14:17], v[180:183], v[204:207], v[14:17]
	v_mfma_f32_16x16x32_bf16 v[6:9], v[172:175], v[212:215], v[6:9]
	v_mfma_f32_16x16x32_bf16 v[2:5], v[180:183], v[212:215], v[2:5]
	s_barrier
	s_add_i32 s18, 0, 0x18000
	v_add_u32_e32 v159, s18, v154
	s_add_i32 s19, 0, 0x1c000
	ds_read_b128 v[146:149], v159
	ds_read_b128 v[150:153], v159 offset:1024
	ds_read_b128 v[160:163], v159 offset:2048
	ds_read_b128 v[164:167], v159 offset:3072
	v_add_u32_e32 v159, s19, v154
	ds_read_b128 v[168:171], v159
	ds_read_b128 v[172:175], v159 offset:1024
	ds_read_b128 v[176:179], v159 offset:2048
	ds_read_b128 v[180:183], v159 offset:3072
	s_add_u32 s46, s46, 0x40000
	s_addc_u32 s47, s47, 0
	s_mov_b32 m0, s58
	ds_read_b128 v[184:187], v158 offset:32768
	ds_read_b128 v[188:191], v158 offset:33792
	ds_read_b128 v[192:195], v158 offset:34816
	ds_read_b128 v[196:199], v158 offset:35840
	ds_read_b128 v[200:203], v158 offset:36864
	ds_read_b128 v[204:207], v158 offset:37888
	ds_read_b128 v[208:211], v158 offset:38912
	ds_read_b128 v[212:215], v158 offset:39936
	global_load_lds_dwordx4 v136, s[46:47]
	s_mov_b32 m0, s59
	s_nop 0
	global_load_lds_dwordx4 v132, s[46:47]
	s_waitcnt vmcnt(8)
	s_waitcnt lgkmcnt(0)
	s_barrier
	s_waitcnt lgkmcnt(0)
	v_mfma_f32_16x16x32_bf16 v[126:129], v[146:149], v[184:187], v[126:129]
	v_mfma_f32_16x16x32_bf16 v[122:125], v[160:163], v[184:187], v[122:125]
	v_mfma_f32_16x16x32_bf16 v[114:117], v[146:149], v[192:195], v[114:117]
	v_mfma_f32_16x16x32_bf16 v[106:109], v[160:163], v[192:195], v[106:109]
	v_mfma_f32_16x16x32_bf16 v[98:101], v[146:149], v[200:203], v[98:101]
	v_mfma_f32_16x16x32_bf16 v[90:93], v[160:163], v[200:203], v[90:93]
	v_mfma_f32_16x16x32_bf16 v[82:85], v[146:149], v[208:211], v[82:85]
	v_mfma_f32_16x16x32_bf16 v[74:77], v[160:163], v[208:211], v[74:77]
	v_mfma_f32_16x16x32_bf16 v[126:129], v[150:153], v[188:191], v[126:129]
	v_mfma_f32_16x16x32_bf16 v[122:125], v[164:167], v[188:191], v[122:125]
	v_mfma_f32_16x16x32_bf16 v[114:117], v[150:153], v[196:199], v[114:117]
	v_mfma_f32_16x16x32_bf16 v[106:109], v[164:167], v[196:199], v[106:109]
	v_mfma_f32_16x16x32_bf16 v[98:101], v[150:153], v[204:207], v[98:101]
	v_mfma_f32_16x16x32_bf16 v[90:93], v[164:167], v[204:207], v[90:93]
	v_mfma_f32_16x16x32_bf16 v[82:85], v[150:153], v[212:215], v[82:85]
	v_mfma_f32_16x16x32_bf16 v[74:77], v[164:167], v[212:215], v[74:77]
	v_mfma_f32_16x16x32_bf16 v[118:121], v[168:171], v[184:187], v[118:121]
	v_mfma_f32_16x16x32_bf16 v[110:113], v[176:179], v[184:187], v[110:113]
	v_mfma_f32_16x16x32_bf16 v[102:105], v[168:171], v[192:195], v[102:105]
	v_mfma_f32_16x16x32_bf16 v[94:97], v[176:179], v[192:195], v[94:97]
	v_mfma_f32_16x16x32_bf16 v[86:89], v[168:171], v[200:203], v[86:89]
	v_mfma_f32_16x16x32_bf16 v[78:81], v[176:179], v[200:203], v[78:81]
	v_mfma_f32_16x16x32_bf16 v[70:73], v[168:171], v[208:211], v[70:73]
	v_mfma_f32_16x16x32_bf16 v[66:69], v[176:179], v[208:211], v[66:69]
	v_mfma_f32_16x16x32_bf16 v[118:121], v[172:175], v[188:191], v[118:121]
	v_mfma_f32_16x16x32_bf16 v[110:113], v[180:183], v[188:191], v[110:113]
	v_mfma_f32_16x16x32_bf16 v[102:105], v[172:175], v[196:199], v[102:105]
	v_mfma_f32_16x16x32_bf16 v[94:97], v[180:183], v[196:199], v[94:97]
	v_mfma_f32_16x16x32_bf16 v[86:89], v[172:175], v[204:207], v[86:89]
	v_mfma_f32_16x16x32_bf16 v[78:81], v[180:183], v[204:207], v[78:81]
	v_mfma_f32_16x16x32_bf16 v[70:73], v[172:175], v[212:215], v[70:73]
	v_mfma_f32_16x16x32_bf16 v[66:69], v[180:183], v[212:215], v[66:69]
	s_barrier
; #define PG8_STAGE(bufoff, gbase, voff) do { _Pragma("unroll") for (int _i = 0; _i < 2; ++_i) \
;         __builtin_amdgcn_global_load_lds((const unsigned*)((const char*)(gbase) + (voff)[_i]), (PG8_LAS unsigned*)(lds + (bufoff) + ldsw + _i * 8192), 16, 0, 0); } while (0)
; #define PG8_LDA(dst, b, h) do { _Pragma("unroll") for (int m = 0; m < 4; ++m) _Pragma("unroll") for (int k = 0; k < 2; ++k) dst[m][k] = *(const PG8_LAS bf16x8*)(lds + PG8_SA(b, h) + aoff + m * 2048 + k * 1024); } while (0)
; #define PG8_MMA(ai, bj, At, Bt) do { __builtin_amdgcn_s_setprio(1); _Pragma("unroll") for (int m = 0; m < 4; ++m) _Pragma("unroll") for (int n = 0; n < 2; ++n) _Pragma("unroll") for (int k = 0; k < 2; ++k) \
;         acc[ai][bj][m][n] = __builtin_amdgcn_mfma_f32_16x16x32_bf16(Bt[n][k], At[m][k], acc[ai][bj][m][n], 0, 0, 0); __builtin_amdgcn_s_setprio(0); } while (0)
; #define PG8_WAIT_V(n) asm volatile("s_waitcnt vmcnt(" #n ")" ::: "memory")
; #define PG8_WAIT_L(n) asm volatile("s_waitcnt lgkmcnt(" #n ")" ::: "memory")
; #define PG8_BAR __builtin_amdgcn_s_barrier()
; #define PG8_SCHED __builtin_amdgcn_sched_barrier(0)
; template <class Epi, class Sched, bool ALIGN_EPI = false, bool SP2 = false>
; __device__ __forceinline__ void gemm_phase(PG8_LAS unsigned char* lds, const Gemm g, const Sched& S, const Epi& E) {
;     ...
;         for (int t = 0; t < nt; t += 2) {
;             const bool last = (t == nt - 2);
;             const char* a1 = cA + (size_t)(t + 1) * kstep;
;             const char* a2 = last ? nA : cA + (size_t)(t + 2) * kstep; const char* b2 = last ? nB : cB + (size_t)(t + 2) * kstep;
;     ...
;             PG8_LDA(At, 1, 1); PG8_STAGE(PG8_SB(1, 0), b3, voffB); PG8_STAGE(PG8_SB(1, 1), b3 + hB, voffB); PG8_STAGE(PG8_SA(1, 0), a3, voffA);
;             PG8_WAIT_V(8); PG8_WAIT_L(0); PG8_BAR; PG8_MMA(1, 0, At, B0); PG8_MMA(1, 1, At, B1); PG8_BAR; PG8_SCHED;
	s_add_i32 s18, s18, s52
	s_mov_b32 m0, s18
	ds_read_b128 v[184:187], v158 offset:49152
	ds_read_b128 v[188:191], v158 offset:50176
	ds_read_b128 v[192:195], v158 offset:51200
	ds_read_b128 v[196:199], v158 offset:52224
	ds_read_b128 v[200:203], v158 offset:53248
	ds_read_b128 v[204:207], v158 offset:54272
	ds_read_b128 v[208:211], v158 offset:55296
	ds_read_b128 v[212:215], v158 offset:56320
	global_load_lds_dwordx4 v134, s[78:79]
	s_add_i32 m0, s18, 0x2000
	s_add_u32 s44, s44, 0x40080
	s_addc_u32 s45, s45, 0
	s_add_i32 s18, s19, s52
	global_load_lds_dwordx4 v130, s[78:79]
	s_mov_b32 m0, s18
	s_nop 0
	global_load_lds_dwordx4 v134, s[44:45]
	s_add_i32 m0, s18, 0x2000
	s_nop 0
	global_load_lds_dwordx4 v130, s[44:45]
	s_mov_b32 m0, s60
	s_nop 0
	global_load_lds_dwordx4 v136, s[80:81]
	s_mov_b32 m0, s61
	s_nop 0
	global_load_lds_dwordx4 v132, s[80:81]
	s_waitcnt vmcnt(8)
	s_waitcnt lgkmcnt(0)
	s_barrier
	s_waitcnt lgkmcnt(0)
	v_mfma_f32_16x16x32_bf16 v[62:65], v[146:149], v[184:187], v[62:65]
	v_mfma_f32_16x16x32_bf16 v[58:61], v[160:163], v[184:187], v[58:61]
	v_mfma_f32_16x16x32_bf16 v[50:53], v[146:149], v[192:195], v[50:53]
	v_mfma_f32_16x16x32_bf16 v[42:45], v[160:163], v[192:195], v[42:45]
	v_mfma_f32_16x16x32_bf16 v[34:37], v[146:149], v[200:203], v[34:37]
	v_mfma_f32_16x16x32_bf16 v[26:29], v[160:163], v[200:203], v[26:29]
	v_mfma_f32_16x16x32_bf16 v[18:21], v[146:149], v[208:211], v[18:21]
	v_mfma_f32_16x16x32_bf16 v[10:13], v[160:163], v[208:211], v[10:13]
	v_mfma_f32_16x16x32_bf16 v[62:65], v[150:153], v[188:191], v[62:65]
	v_mfma_f32_16x16x32_bf16 v[58:61], v[164:167], v[188:191], v[58:61]
	v_mfma_f32_16x16x32_bf16 v[50:53], v[150:153], v[196:199], v[50:53]
	v_mfma_f32_16x16x32_bf16 v[42:45], v[164:167], v[196:199], v[42:45]
	v_mfma_f32_16x16x32_bf16 v[34:37], v[150:153], v[204:207], v[34:37]
	v_mfma_f32_16x16x32_bf16 v[26:29], v[164:167], v[204:207], v[26:29]
	v_mfma_f32_16x16x32_bf16 v[18:21], v[150:153], v[212:215], v[18:21]
	v_mfma_f32_16x16x32_bf16 v[10:13], v[164:167], v[212:215], v[10:13]
	v_mfma_f32_16x16x32_bf16 v[54:57], v[168:171], v[184:187], v[54:57]
	v_mfma_f32_16x16x32_bf16 v[46:49], v[176:179], v[184:187], v[46:49]
	v_mfma_f32_16x16x32_bf16 v[38:41], v[168:171], v[192:195], v[38:41]
	v_mfma_f32_16x16x32_bf16 v[30:33], v[176:179], v[192:195], v[30:33]
	v_mfma_f32_16x16x32_bf16 v[22:25], v[168:171], v[200:203], v[22:25]
	v_mfma_f32_16x16x32_bf16 v[14:17], v[176:179], v[200:203], v[14:17]
	v_mfma_f32_16x16x32_bf16 v[6:9], v[168:171], v[208:211], v[6:9]
	v_mfma_f32_16x16x32_bf16 v[2:5], v[176:179], v[208:211], v[2:5]
	v_mfma_f32_16x16x32_bf16 v[54:57], v[172:175], v[188:191], v[54:57]
	v_mfma_f32_16x16x32_bf16 v[46:49], v[180:183], v[188:191], v[46:49]
	v_mfma_f32_16x16x32_bf16 v[38:41], v[172:175], v[196:199], v[38:41]
	v_mfma_f32_16x16x32_bf16 v[30:33], v[180:183], v[196:199], v[30:33]
	v_mfma_f32_16x16x32_bf16 v[22:25], v[172:175], v[204:207], v[22:25]
	v_mfma_f32_16x16x32_bf16 v[14:17], v[180:183], v[204:207], v[14:17]
	v_mfma_f32_16x16x32_bf16 v[6:9], v[172:175], v[212:215], v[6:9]
	v_mfma_f32_16x16x32_bf16 v[2:5], v[180:183], v[212:215], v[2:5]
	s_barrier
	s_add_i32 s72, s72, 2
	s_add_u32 s42, s42, 0x100
	s_addc_u32 s43, s43, 0
	s_add_u32 s70, s70, 0x100
	s_addc_u32 s71, s71, 0
	s_cmp_gt_u32 s72, 13

; #define PG8_STAGE(bufoff, gbase, voff) do { _Pragma("unroll") for (int _i = 0; _i < 2; ++_i) \
;         __builtin_amdgcn_global_load_lds((const unsigned*)((const char*)(gbase) + (voff)[_i]), (PG8_LAS unsigned*)(lds + (bufoff) + ldsw + _i * 8192), 16, 0, 0); } while (0)
; #define PG8_LDA(dst, b, h) do { _Pragma("unroll") for (int m = 0; m < 4; ++m) _Pragma("unroll") for (int k = 0; k < 2; ++k) dst[m][k] = *(const PG8_LAS bf16x8*)(lds + PG8_SA(b, h) + aoff + m * 2048 + k * 1024); } while (0)
; #define PG8_WAIT_V(n) asm volatile("s_waitcnt vmcnt(" #n ")" ::: "memory")
; #define PG8_WAIT_L(n) asm volatile("s_waitcnt lgkmcnt(" #n ")" ::: "memory")
; #define PG8_BAR __builtin_amdgcn_s_barrier()
; template <class Epi, class Sched, bool ALIGN_EPI = false, bool SP2 = false>
; __device__ __forceinline__ void gemm_phase(PG8_LAS unsigned char* lds, const Gemm g, const Sched& S, const Epi& E) {
;     ...
;         const bool has_next = S.next(ui + 1, nxt);
;         const char* nA = has_next ? (const char*)g.A + (size_t)nxt.pm * tA + (size_t)nxt.pn * pnA : cA; const char* nB = has_next ? (const char*)g.Bt + (size_t)nxt.pn * tB : cB;
; #pragma nounroll
;         for (int t = 0; t < nt; t += 2) {
;             const bool last = (t == nt - 2);
;             const char* a1 = cA + (size_t)(t + 1) * kstep;
;             const char* a2 = last ? nA : cA + (size_t)(t + 2) * kstep; const char* b2 = last ? nB : cB + (size_t)(t + 2) * kstep;
;             const char* a3 = a2 + kstep; const char* b3 = b2 + kstep;
;             if (last && has_next) S.a_ready(nxt);
;             if constexpr (SP2) {
;             PG8_LDB(B0, 0, 0); PG8_LDB(B1, 0, 1); PG8_SCHED; PG8_LDA(At, 0, 0); PG8_STAGE(PG8_SA(1, 1), a1 + hA, voffA);
;             PG8_WAIT_V(8); PG8_WAIT_L(0); PG8_BAR; PG8_MMA(0, 0, At, B0); PG8_MMA(0, 1, At, B1); PG8_BAR; PG8_SCHED;
;             PG8_LDA(At, 0, 1); PG8_STAGE(PG8_SB(0, 0), b2, voffB); PG8_STAGE(PG8_SB(0, 1), b2 + hB, voffB); PG8_STAGE(PG8_SA(0, 0), a2, voffA);
;             PG8_WAIT_V(8); PG8_WAIT_L(0); PG8_BAR; PG8_MMA(1, 0, At, B0); PG8_MMA(1, 1, At, B1); PG8_BAR; PG8_SCHED;
;     ...
; #pragma unroll
;         for (int a = 0; a < 2; ++a)
; #pragma unroll
;             for (int b = 0; b < 2; ++b)
; #pragma unroll
;                 for (int m = 0; m < 4; ++m)
; #pragma unroll
;                     for (int n = 0; n < 2; ++n) acc[a][b][m][n] = (f32x4){0.f, 0.f, 0.f, 0.f};
.LBB0_887:
	s_ashr_i32 s25, s24, 31
	s_lshl_b64 s[38:39], s[24:25], 20
	s_add_u32 s38, s33, s38
	s_addc_u32 s39, s51, s39
	s_and_b64 s[40:41], s[6:7], exec
	s_cselect_b32 s25, s39, s45
	s_cselect_b32 s70, s38, s44
	s_ashr_i32 s23, s22, 31
	s_lshl_b64 s[40:41], s[22:23], 20
	s_add_u32 s40, s52, s40
	s_addc_u32 s41, s53, s41
	s_and_b64 s[48:49], s[6:7], exec
	s_cselect_b32 s23, s41, s47
	s_cselect_b32 s71, s40, s46
	s_add_u32 s44, s44, 0x80080
	s_addc_u32 s45, s45, 0
	s_add_u32 s72, s46, 0x100
	v_mov_b32_e32 v2, 0
	s_addc_u32 s73, s47, 0
	s_mov_b32 s74, -2
	v_mov_b32_e32 v3, v2
	ds_read_b128 v[130:133], v172
	ds_read_b128 v[134:137], v172 offset:1024
	ds_read_b128 v[138:141], v172 offset:2048
	ds_read_b128 v[142:145], v172 offset:3072
	ds_read_b128 v[162:165], v173
	ds_read_b128 v[166:169], v173 offset:1024
	ds_read_b128 v[176:179], v173 offset:2048
	ds_read_b128 v[180:183], v173 offset:3072
	s_add_u32 s18, s44, 0xfff80080
	s_addc_u32 s19, s45, -1
	s_cmp_eq_u32 s74, 28
	s_cselect_b32 s49, s25, s19
	s_cselect_b32 s48, s70, s18
	s_cselect_b32 s47, s23, s73
	s_cselect_b32 s46, s71, s72
	s_add_i32 m0, s43, 0xc000
	ds_read_b128 v[184:187], v174
	ds_read_b128 v[188:191], v174 offset:1024
	ds_read_b128 v[192:195], v174 offset:2048
	ds_read_b128 v[196:199], v174 offset:3072
	ds_read_b128 v[200:203], v174 offset:4096
	ds_read_b128 v[204:207], v174 offset:5120
	ds_read_b128 v[208:211], v174 offset:6144
	ds_read_b128 v[212:215], v174 offset:7168
	global_load_lds_dwordx4 v154, s[44:45]
	s_add_i32 m0, s43, 0xe000
	s_nop 0
	global_load_lds_dwordx4 v156, s[44:45]
	s_waitcnt vmcnt(8)
	s_waitcnt lgkmcnt(0)
	s_barrier
	s_waitcnt lgkmcnt(0)
	v_mfma_f32_16x16x32_bf16 v[126:129], v[130:133], v[184:187], 0
	v_mfma_f32_16x16x32_bf16 v[122:125], v[138:141], v[184:187], 0
	v_mfma_f32_16x16x32_bf16 v[110:113], v[130:133], v[192:195], 0
	v_mfma_f32_16x16x32_bf16 v[106:109], v[138:141], v[192:195], 0
	v_mfma_f32_16x16x32_bf16 v[94:97], v[130:133], v[200:203], 0
	v_mfma_f32_16x16x32_bf16 v[90:93], v[138:141], v[200:203], 0
	v_mfma_f32_16x16x32_bf16 v[78:81], v[130:133], v[208:211], 0
	v_mfma_f32_16x16x32_bf16 v[74:77], v[138:141], v[208:211], 0
	v_mfma_f32_16x16x32_bf16 v[126:129], v[134:137], v[188:191], v[126:129]
	v_mfma_f32_16x16x32_bf16 v[122:125], v[142:145], v[188:191], v[122:125]
	v_mfma_f32_16x16x32_bf16 v[110:113], v[134:137], v[196:199], v[110:113]
	v_mfma_f32_16x16x32_bf16 v[106:109], v[142:145], v[196:199], v[106:109]
	v_mfma_f32_16x16x32_bf16 v[94:97], v[134:137], v[204:207], v[94:97]
	v_mfma_f32_16x16x32_bf16 v[90:93], v[142:145], v[204:207], v[90:93]
	v_mfma_f32_16x16x32_bf16 v[78:81], v[134:137], v[212:215], v[78:81]
	v_mfma_f32_16x16x32_bf16 v[74:77], v[142:145], v[212:215], v[74:77]
	v_mfma_f32_16x16x32_bf16 v[118:121], v[162:165], v[184:187], 0
	v_mfma_f32_16x16x32_bf16 v[114:117], v[176:179], v[184:187], 0
	v_mfma_f32_16x16x32_bf16 v[102:105], v[162:165], v[192:195], 0
	v_mfma_f32_16x16x32_bf16 v[98:101], v[176:179], v[192:195], 0
	v_mfma_f32_16x16x32_bf16 v[86:89], v[162:165], v[200:203], 0
	v_mfma_f32_16x16x32_bf16 v[82:85], v[176:179], v[200:203], 0
	v_mfma_f32_16x16x32_bf16 v[70:73], v[162:165], v[208:211], 0
	v_mfma_f32_16x16x32_bf16 v[66:69], v[176:179], v[208:211], 0
	v_mfma_f32_16x16x32_bf16 v[118:121], v[166:169], v[188:191], v[118:121]
	v_mfma_f32_16x16x32_bf16 v[114:117], v[180:183], v[188:191], v[114:117]
	v_mfma_f32_16x16x32_bf16 v[102:105], v[166:169], v[196:199], v[102:105]
	v_mfma_f32_16x16x32_bf16 v[98:101], v[180:183], v[196:199], v[98:101]
	v_mfma_f32_16x16x32_bf16 v[86:89], v[166:169], v[204:207], v[86:89]
	v_mfma_f32_16x16x32_bf16 v[82:85], v[180:183], v[204:207], v[82:85]
	v_mfma_f32_16x16x32_bf16 v[70:73], v[166:169], v[212:215], v[70:73]
	v_mfma_f32_16x16x32_bf16 v[66:69], v[180:183], v[212:215], v[66:69]
	s_barrier
	s_add_i32 s18, s66, s58
	s_add_u32 s78, s46, s16
	s_addc_u32 s79, s47, s17
	s_mov_b32 m0, s18
	ds_read_b128 v[184:187], v174 offset:16384
	ds_read_b128 v[188:191], v174 offset:17408
	ds_read_b128 v[192:195], v174 offset:18432
	ds_read_b128 v[196:199], v174 offset:19456
	ds_read_b128 v[200:203], v174 offset:20480
	ds_read_b128 v[204:207], v174 offset:21504
	ds_read_b128 v[208:211], v174 offset:22528
	ds_read_b128 v[212:215], v174 offset:23552
	global_load_lds_dwordx4 v150, s[46:47]
	s_add_i32 m0, s18, 0x2000
	s_add_u32 s76, s46, 0x80000
	s_addc_u32 s77, s47, 0
	s_add_i32 s18, s67, s58
	global_load_lds_dwordx4 v146, s[46:47]
	s_mov_b32 m0, s18
	s_nop 0
	global_load_lds_dwordx4 v150, s[76:77]
	s_add_i32 m0, s18, 0x2000
	s_nop 0
	global_load_lds_dwordx4 v146, s[76:77]
	s_add_u32 s80, s48, s16
	s_addc_u32 s81, s49, s17
	s_mov_b32 m0, s43
	s_nop 0
	global_load_lds_dwordx4 v152, s[48:49]
	s_mov_b32 m0, s59
	s_nop 0
	global_load_lds_dwordx4 v148, s[48:49]
	s_waitcnt vmcnt(8)
	s_waitcnt lgkmcnt(0)
	s_barrier
; #define PG8_STAGE(bufoff, gbase, voff) do { _Pragma("unroll") for (int _i = 0; _i < 2; ++_i) \
;         __builtin_amdgcn_global_load_lds((const unsigned*)((const char*)(gbase) + (voff)[_i]), (PG8_LAS unsigned*)(lds + (bufoff) + ldsw + _i * 8192), 16, 0, 0); } while (0)
; #define PG8_LDA(dst, b, h) do { _Pragma("unroll") for (int m = 0; m < 4; ++m) _Pragma("unroll") for (int k = 0; k < 2; ++k) dst[m][k] = *(const PG8_LAS bf16x8*)(lds + PG8_SA(b, h) + aoff + m * 2048 + k * 1024); } while (0)
; #define PG8_LDB(dst, b, h) do { _Pragma("unroll") for (int n = 0; n < 2; ++n) _Pragma("unroll") for (int k = 0; k < 2; ++k) dst[n][k] = *(const PG8_LAS bf16x8*)(lds + PG8_SB(b, h) + boff + n * 2048 + k * 1024); } while (0)
; #define PG8_MMA(ai, bj, At, Bt) do { __builtin_amdgcn_s_setprio(1); _Pragma("unroll") for (int m = 0; m < 4; ++m) _Pragma("unroll") for (int n = 0; n < 2; ++n) _Pragma("unroll") for (int k = 0; k < 2; ++k) \
;         acc[ai][bj][m][n] = __builtin_amdgcn_mfma_f32_16x16x32_bf16(Bt[n][k], At[m][k], acc[ai][bj][m][n], 0, 0, 0); __builtin_amdgcn_s_setprio(0); } while (0)
; #define PG8_WAIT_V(n) asm volatile("s_waitcnt vmcnt(" #n ")" ::: "memory")
; #define PG8_WAIT_L(n) asm volatile("s_waitcnt lgkmcnt(" #n ")" ::: "memory")
; #define PG8_BAR __builtin_amdgcn_s_barrier()
; #define PG8_SCHED __builtin_amdgcn_sched_barrier(0)
; template <class Epi, class Sched, bool ALIGN_EPI = false, bool SP2 = false>
; __device__ __forceinline__ void gemm_phase(PG8_LAS unsigned char* lds, const Gemm g, const Sched& S, const Epi& E) {
;     ...
;             PG8_WAIT_V(8); PG8_WAIT_L(0); PG8_BAR; PG8_MMA(0, 0, At, B0); PG8_MMA(0, 1, At, B1); PG8_BAR; PG8_SCHED;
;             PG8_LDA(At, 0, 1); PG8_STAGE(PG8_SB(0, 0), b2, voffB); PG8_STAGE(PG8_SB(0, 1), b2 + hB, voffB); PG8_STAGE(PG8_SA(0, 0), a2, voffA);
;             PG8_WAIT_V(8); PG8_WAIT_L(0); PG8_BAR; PG8_MMA(1, 0, At, B0); PG8_MMA(1, 1, At, B1); PG8_BAR; PG8_SCHED;
;             PG8_LDB(B0, 1, 0); PG8_LDB(B1, 1, 1); PG8_SCHED; PG8_LDA(At, 1, 0); PG8_STAGE(PG8_SA(0, 1), a2 + hA, voffA);
;             PG8_WAIT_V(8); PG8_WAIT_L(0); PG8_BAR; PG8_MMA(0, 0, At, B0); PG8_MMA(0, 1, At, B1); PG8_BAR; PG8_SCHED;
	s_waitcnt lgkmcnt(0)
	v_mfma_f32_16x16x32_bf16 v[62:65], v[130:133], v[184:187], 0
	v_mfma_f32_16x16x32_bf16 v[58:61], v[138:141], v[184:187], 0
	v_mfma_f32_16x16x32_bf16 v[46:49], v[130:133], v[192:195], 0
	v_mfma_f32_16x16x32_bf16 v[42:45], v[138:141], v[192:195], 0
	v_mfma_f32_16x16x32_bf16 v[30:33], v[130:133], v[200:203], 0
	v_mfma_f32_16x16x32_bf16 v[26:29], v[138:141], v[200:203], 0
	v_mfma_f32_16x16x32_bf16 v[14:17], v[130:133], v[208:211], 0
	v_mfma_f32_16x16x32_bf16 v[10:13], v[138:141], v[208:211], 0
	v_mfma_f32_16x16x32_bf16 v[62:65], v[134:137], v[188:191], v[62:65]
	v_mfma_f32_16x16x32_bf16 v[58:61], v[142:145], v[188:191], v[58:61]
	v_mfma_f32_16x16x32_bf16 v[46:49], v[134:137], v[196:199], v[46:49]
	v_mfma_f32_16x16x32_bf16 v[42:45], v[142:145], v[196:199], v[42:45]
	v_mfma_f32_16x16x32_bf16 v[30:33], v[134:137], v[204:207], v[30:33]
	v_mfma_f32_16x16x32_bf16 v[26:29], v[142:145], v[204:207], v[26:29]
	v_mfma_f32_16x16x32_bf16 v[14:17], v[134:137], v[212:215], v[14:17]
	v_mfma_f32_16x16x32_bf16 v[10:13], v[142:145], v[212:215], v[10:13]
	v_mfma_f32_16x16x32_bf16 v[54:57], v[162:165], v[184:187], 0
	v_mfma_f32_16x16x32_bf16 v[50:53], v[176:179], v[184:187], 0
	v_mfma_f32_16x16x32_bf16 v[38:41], v[162:165], v[192:195], 0
	v_mfma_f32_16x16x32_bf16 v[34:37], v[176:179], v[192:195], 0
	v_mfma_f32_16x16x32_bf16 v[22:25], v[162:165], v[200:203], 0
	v_mfma_f32_16x16x32_bf16 v[18:21], v[176:179], v[200:203], 0
	v_mfma_f32_16x16x32_bf16 v[6:9], v[162:165], v[208:211], 0
	v_mfma_f32_16x16x32_bf16 v[2:5], v[176:179], v[208:211], 0
	v_mfma_f32_16x16x32_bf16 v[54:57], v[166:169], v[188:191], v[54:57]
	v_mfma_f32_16x16x32_bf16 v[50:53], v[180:183], v[188:191], v[50:53]
	v_mfma_f32_16x16x32_bf16 v[38:41], v[166:169], v[196:199], v[38:41]
	v_mfma_f32_16x16x32_bf16 v[34:37], v[180:183], v[196:199], v[34:37]
	v_mfma_f32_16x16x32_bf16 v[22:25], v[166:169], v[204:207], v[22:25]
	v_mfma_f32_16x16x32_bf16 v[18:21], v[180:183], v[204:207], v[18:21]
	v_mfma_f32_16x16x32_bf16 v[6:9], v[166:169], v[212:215], v[6:9]
	v_mfma_f32_16x16x32_bf16 v[2:5], v[180:183], v[212:215], v[2:5]
	s_barrier
	s_add_i32 s18, 0, 0x18000
	s_add_i32 s19, 0, 0x1c000
	v_add_u32_e32 v142, s18, v170
	v_add_u32_e32 v175, s19, v170
	ds_read_b128 v[130:133], v142
	ds_read_b128 v[134:137], v142 offset:1024
	ds_read_b128 v[138:141], v142 offset:2048
	ds_read_b128 v[142:145], v142 offset:3072
	ds_read_b128 v[162:165], v175
	ds_read_b128 v[166:169], v175 offset:1024
	ds_read_b128 v[176:179], v175 offset:2048
	ds_read_b128 v[180:183], v175 offset:3072
	s_add_u32 s48, s48, 0x80000
	s_addc_u32 s49, s49, 0
	s_mov_b32 m0, s60
	ds_read_b128 v[184:187], v174 offset:32768
	ds_read_b128 v[188:191], v174 offset:33792
	ds_read_b128 v[192:195], v174 offset:34816
	ds_read_b128 v[196:199], v174 offset:35840
	ds_read_b128 v[200:203], v174 offset:36864
	ds_read_b128 v[204:207], v174 offset:37888
	ds_read_b128 v[208:211], v174 offset:38912
	ds_read_b128 v[212:215], v174 offset:39936
	global_load_lds_dwordx4 v152, s[48:49]
	s_mov_b32 m0, s61
	s_nop 0
	global_load_lds_dwordx4 v148, s[48:49]
	s_waitcnt vmcnt(8)
	s_waitcnt lgkmcnt(0)
	s_barrier
	s_waitcnt lgkmcnt(0)
	v_mfma_f32_16x16x32_bf16 v[126:129], v[130:133], v[184:187], v[126:129]
	v_mfma_f32_16x16x32_bf16 v[122:125], v[138:141], v[184:187], v[122:125]
	v_mfma_f32_16x16x32_bf16 v[110:113], v[130:133], v[192:195], v[110:113]
	v_mfma_f32_16x16x32_bf16 v[106:109], v[138:141], v[192:195], v[106:109]
	v_mfma_f32_16x16x32_bf16 v[94:97], v[130:133], v[200:203], v[94:97]
	v_mfma_f32_16x16x32_bf16 v[90:93], v[138:141], v[200:203], v[90:93]
	v_mfma_f32_16x16x32_bf16 v[78:81], v[130:133], v[208:211], v[78:81]
	v_mfma_f32_16x16x32_bf16 v[74:77], v[138:141], v[208:211], v[74:77]
	v_mfma_f32_16x16x32_bf16 v[126:129], v[134:137], v[188:191], v[126:129]
	v_mfma_f32_16x16x32_bf16 v[122:125], v[142:145], v[188:191], v[122:125]
	v_mfma_f32_16x16x32_bf16 v[110:113], v[134:137], v[196:199], v[110:113]
	v_mfma_f32_16x16x32_bf16 v[106:109], v[142:145], v[196:199], v[106:109]
	v_mfma_f32_16x16x32_bf16 v[94:97], v[134:137], v[204:207], v[94:97]
	v_mfma_f32_16x16x32_bf16 v[90:93], v[142:145], v[204:207], v[90:93]
	v_mfma_f32_16x16x32_bf16 v[78:81], v[134:137], v[212:215], v[78:81]
	v_mfma_f32_16x16x32_bf16 v[74:77], v[142:145], v[212:215], v[74:77]
	v_mfma_f32_16x16x32_bf16 v[118:121], v[162:165], v[184:187], v[118:121]
	v_mfma_f32_16x16x32_bf16 v[114:117], v[176:179], v[184:187], v[114:117]
	v_mfma_f32_16x16x32_bf16 v[102:105], v[162:165], v[192:195], v[102:105]
	v_mfma_f32_16x16x32_bf16 v[98:101], v[176:179], v[192:195], v[98:101]
	v_mfma_f32_16x16x32_bf16 v[86:89], v[162:165], v[200:203], v[86:89]
	v_mfma_f32_16x16x32_bf16 v[82:85], v[176:179], v[200:203], v[82:85]
	v_mfma_f32_16x16x32_bf16 v[70:73], v[162:165], v[208:211], v[70:73]
	v_mfma_f32_16x16x32_bf16 v[66:69], v[176:179], v[208:211], v[66:69]
	v_mfma_f32_16x16x32_bf16 v[118:121], v[166:169], v[188:191], v[118:121]
	v_mfma_f32_16x16x32_bf16 v[114:117], v[180:183], v[188:191], v[114:117]
	v_mfma_f32_16x16x32_bf16 v[102:105], v[166:169], v[196:199], v[102:105]
	v_mfma_f32_16x16x32_bf16 v[98:101], v[180:183], v[196:199], v[98:101]
	v_mfma_f32_16x16x32_bf16 v[86:89], v[166:169], v[204:207], v[86:89]
	v_mfma_f32_16x16x32_bf16 v[82:85], v[180:183], v[204:207], v[82:85]
	v_mfma_f32_16x16x32_bf16 v[70:73], v[166:169], v[212:215], v[70:73]
	v_mfma_f32_16x16x32_bf16 v[66:69], v[180:183], v[212:215], v[66:69]
	s_barrier
; #define PG8_STAGE(bufoff, gbase, voff) do { _Pragma("unroll") for (int _i = 0; _i < 2; ++_i) \
;         __builtin_amdgcn_global_load_lds((const unsigned*)((const char*)(gbase) + (voff)[_i]), (PG8_LAS unsigned*)(lds + (bufoff) + ldsw + _i * 8192), 16, 0, 0); } while (0)
; #define PG8_LDA(dst, b, h) do { _Pragma("unroll") for (int m = 0; m < 4; ++m) _Pragma("unroll") for (int k = 0; k < 2; ++k) dst[m][k] = *(const PG8_LAS bf16x8*)(lds + PG8_SA(b, h) + aoff + m * 2048 + k * 1024); } while (0)
; #define PG8_MMA(ai, bj, At, Bt) do { __builtin_amdgcn_s_setprio(1); _Pragma("unroll") for (int m = 0; m < 4; ++m) _Pragma("unroll") for (int n = 0; n < 2; ++n) _Pragma("unroll") for (int k = 0; k < 2; ++k) \
;         acc[ai][bj][m][n] = __builtin_amdgcn_mfma_f32_16x16x32_bf16(Bt[n][k], At[m][k], acc[ai][bj][m][n], 0, 0, 0); __builtin_amdgcn_s_setprio(0); } while (0)
; #define PG8_WAIT_V(n) asm volatile("s_waitcnt vmcnt(" #n ")" ::: "memory")
; #define PG8_WAIT_L(n) asm volatile("s_waitcnt lgkmcnt(" #n ")" ::: "memory")
; #define PG8_BAR __builtin_amdgcn_s_barrier()
; #define PG8_SCHED __builtin_amdgcn_sched_barrier(0)
; template <class Epi, class Sched, bool ALIGN_EPI = false, bool SP2 = false>
; __device__ __forceinline__ void gemm_phase(PG8_LAS unsigned char* lds, const Gemm g, const Sched& S, const Epi& E) {
;     ...
;         for (int t = 0; t < nt; t += 2) {
;             const bool last = (t == nt - 2);
;             const char* a1 = cA + (size_t)(t + 1) * kstep;
;             const char* a2 = last ? nA : cA + (size_t)(t + 2) * kstep; const char* b2 = last ? nB : cB + (size_t)(t + 2) * kstep;
;     ...
;             PG8_LDA(At, 1, 1); PG8_STAGE(PG8_SB(1, 0), b3, voffB); PG8_STAGE(PG8_SB(1, 1), b3 + hB, voffB); PG8_STAGE(PG8_SA(1, 0), a3, voffA);
;             PG8_WAIT_V(8); PG8_WAIT_L(0); PG8_BAR; PG8_MMA(1, 0, At, B0); PG8_MMA(1, 1, At, B1); PG8_BAR; PG8_SCHED;
	s_add_i32 s18, s18, s58
	s_mov_b32 m0, s18
	ds_read_b128 v[184:187], v174 offset:49152
	ds_read_b128 v[188:191], v174 offset:50176
	ds_read_b128 v[192:195], v174 offset:51200
	ds_read_b128 v[196:199], v174 offset:52224
	ds_read_b128 v[200:203], v174 offset:53248
	ds_read_b128 v[204:207], v174 offset:54272
	ds_read_b128 v[208:211], v174 offset:55296
	ds_read_b128 v[212:215], v174 offset:56320
	global_load_lds_dwordx4 v150, s[78:79]
	s_add_i32 m0, s18, 0x2000
	s_add_u32 s46, s46, 0x80080
	s_addc_u32 s47, s47, 0
	s_add_i32 s18, s19, s58
	global_load_lds_dwordx4 v146, s[78:79]
	s_mov_b32 m0, s18
	s_nop 0
	global_load_lds_dwordx4 v150, s[46:47]
	s_add_i32 m0, s18, 0x2000
	s_nop 0
	global_load_lds_dwordx4 v146, s[46:47]
	s_mov_b32 m0, s63
	s_nop 0
	global_load_lds_dwordx4 v152, s[80:81]
	s_mov_b32 m0, s64
	s_nop 0
	global_load_lds_dwordx4 v148, s[80:81]
	s_waitcnt vmcnt(8)
	s_waitcnt lgkmcnt(0)
	s_barrier
	s_waitcnt lgkmcnt(0)
	v_mfma_f32_16x16x32_bf16 v[62:65], v[130:133], v[184:187], v[62:65]
	v_mfma_f32_16x16x32_bf16 v[58:61], v[138:141], v[184:187], v[58:61]
	v_mfma_f32_16x16x32_bf16 v[46:49], v[130:133], v[192:195], v[46:49]
	v_mfma_f32_16x16x32_bf16 v[42:45], v[138:141], v[192:195], v[42:45]
	v_mfma_f32_16x16x32_bf16 v[30:33], v[130:133], v[200:203], v[30:33]
	v_mfma_f32_16x16x32_bf16 v[26:29], v[138:141], v[200:203], v[26:29]
	v_mfma_f32_16x16x32_bf16 v[14:17], v[130:133], v[208:211], v[14:17]
	v_mfma_f32_16x16x32_bf16 v[10:13], v[138:141], v[208:211], v[10:13]
	v_mfma_f32_16x16x32_bf16 v[62:65], v[134:137], v[188:191], v[62:65]
	v_mfma_f32_16x16x32_bf16 v[58:61], v[142:145], v[188:191], v[58:61]
	v_mfma_f32_16x16x32_bf16 v[46:49], v[134:137], v[196:199], v[46:49]
	v_mfma_f32_16x16x32_bf16 v[42:45], v[142:145], v[196:199], v[42:45]
	v_mfma_f32_16x16x32_bf16 v[30:33], v[134:137], v[204:207], v[30:33]
	v_mfma_f32_16x16x32_bf16 v[26:29], v[142:145], v[204:207], v[26:29]
	v_mfma_f32_16x16x32_bf16 v[14:17], v[134:137], v[212:215], v[14:17]
	v_mfma_f32_16x16x32_bf16 v[10:13], v[142:145], v[212:215], v[10:13]
	v_mfma_f32_16x16x32_bf16 v[54:57], v[162:165], v[184:187], v[54:57]
	v_mfma_f32_16x16x32_bf16 v[50:53], v[176:179], v[184:187], v[50:53]
	v_mfma_f32_16x16x32_bf16 v[38:41], v[162:165], v[192:195], v[38:41]
	v_mfma_f32_16x16x32_bf16 v[34:37], v[176:179], v[192:195], v[34:37]
	v_mfma_f32_16x16x32_bf16 v[22:25], v[162:165], v[200:203], v[22:25]
	v_mfma_f32_16x16x32_bf16 v[18:21], v[176:179], v[200:203], v[18:21]
	v_mfma_f32_16x16x32_bf16 v[6:9], v[162:165], v[208:211], v[6:9]
	v_mfma_f32_16x16x32_bf16 v[2:5], v[176:179], v[208:211], v[2:5]
	v_mfma_f32_16x16x32_bf16 v[54:57], v[166:169], v[188:191], v[54:57]
	v_mfma_f32_16x16x32_bf16 v[50:53], v[180:183], v[188:191], v[50:53]
	v_mfma_f32_16x16x32_bf16 v[38:41], v[166:169], v[196:199], v[38:41]
	v_mfma_f32_16x16x32_bf16 v[34:37], v[180:183], v[196:199], v[34:37]
	v_mfma_f32_16x16x32_bf16 v[22:25], v[166:169], v[204:207], v[22:25]
	v_mfma_f32_16x16x32_bf16 v[18:21], v[180:183], v[204:207], v[18:21]
	v_mfma_f32_16x16x32_bf16 v[6:9], v[166:169], v[212:215], v[6:9]
	v_mfma_f32_16x16x32_bf16 v[2:5], v[180:183], v[212:215], v[2:5]
	s_barrier
	s_add_i32 s74, s74, 2
	s_add_u32 s44, s44, 0x100
	s_addc_u32 s45, s45, 0
	s_add_u32 s72, s72, 0x100
	s_addc_u32 s73, s73, 0
	s_cmp_gt_u32 s74, 29

; #define PG8_STAGE(bufoff, gbase, voff) do { _Pragma("unroll") for (int _i = 0; _i < 2; ++_i) \
;         __builtin_amdgcn_global_load_lds((const unsigned*)((const char*)(gbase) + (voff)[_i]), (PG8_LAS unsigned*)(lds + (bufoff) + ldsw + _i * 8192), 16, 0, 0); } while (0)
; #define PG8_LDA(dst, b, h) do { _Pragma("unroll") for (int m = 0; m < 4; ++m) _Pragma("unroll") for (int k = 0; k < 2; ++k) dst[m][k] = *(const PG8_LAS bf16x8*)(lds + PG8_SA(b, h) + aoff + m * 2048 + k * 1024); } while (0)
; #define PG8_WAIT_V(n) asm volatile("s_waitcnt vmcnt(" #n ")" ::: "memory")
; #define PG8_WAIT_L(n) asm volatile("s_waitcnt lgkmcnt(" #n ")" ::: "memory")
; #define PG8_BAR __builtin_amdgcn_s_barrier()
; template <class Epi, class Sched, bool ALIGN_EPI = false, bool SP2 = false>
; __device__ __forceinline__ void gemm_phase(PG8_LAS unsigned char* lds, const Gemm g, const Sched& S, const Epi& E) {
;     ...
;         const bool has_next = S.next(ui + 1, nxt);
;         const char* nA = has_next ? (const char*)g.A + (size_t)nxt.pm * tA + (size_t)nxt.pn * pnA : cA; const char* nB = has_next ? (const char*)g.Bt + (size_t)nxt.pn * tB : cB;
; #pragma nounroll
;         for (int t = 0; t < nt; t += 2) {
;             const bool last = (t == nt - 2);
;             const char* a1 = cA + (size_t)(t + 1) * kstep;
;             const char* a2 = last ? nA : cA + (size_t)(t + 2) * kstep; const char* b2 = last ? nB : cB + (size_t)(t + 2) * kstep;
;             const char* a3 = a2 + kstep; const char* b3 = b2 + kstep;
;             if (last && has_next) S.a_ready(nxt);
;             if constexpr (SP2) {
;             PG8_LDB(B0, 0, 0); PG8_LDB(B1, 0, 1); PG8_SCHED; PG8_LDA(At, 0, 0); PG8_STAGE(PG8_SA(1, 1), a1 + hA, voffA);
;             PG8_WAIT_V(8); PG8_WAIT_L(0); PG8_BAR; PG8_MMA(0, 0, At, B0); PG8_MMA(0, 1, At, B1); PG8_BAR; PG8_SCHED;
;             PG8_LDA(At, 0, 1); PG8_STAGE(PG8_SB(0, 0), b2, voffB); PG8_STAGE(PG8_SB(0, 1), b2 + hB, voffB); PG8_STAGE(PG8_SA(0, 0), a2, voffA);
;             PG8_WAIT_V(8); PG8_WAIT_L(0); PG8_BAR; PG8_MMA(1, 0, At, B0); PG8_MMA(1, 1, At, B1); PG8_BAR; PG8_SCHED;
;     ...
; #pragma unroll
;         for (int a = 0; a < 2; ++a)
; #pragma unroll
;             for (int b = 0; b < 2; ++b)
; #pragma unroll
;                 for (int m = 0; m < 4; ++m)
; #pragma unroll
;                     for (int n = 0; n < 2; ++n) acc[a][b][m][n] = (f32x4){0.f, 0.f, 0.f, 0.f};
.LBB0_962:
	s_ashr_i32 s41, s40, 31
	s_lshl_b64 s[42:43], s[40:41], 20
	s_add_u32 s42, s33, s42
	s_addc_u32 s43, s58, s43
	s_and_b64 s[44:45], s[8:9], exec
	s_cselect_b32 s41, s43, s49
	s_cselect_b32 s47, s42, s48
	s_ashr_i32 s39, s38, 31
	s_lshl_b64 s[44:45], s[38:39], 20
	s_add_u32 s44, s59, s44
	s_addc_u32 s45, s60, s45
	s_and_b64 s[52:53], s[8:9], exec
	s_cselect_b32 s39, s45, s51
	s_cselect_b32 s75, s44, s50
	s_add_u32 s48, s48, 0x80080
	s_addc_u32 s49, s49, 0
	s_add_u32 s76, s50, 0x100
	v_mov_b32_e32 v2, 0
	s_addc_u32 s77, s51, 0
	s_mov_b32 s78, -2
	s_waitcnt lgkmcnt(0)
	v_mov_b32_e32 v3, v2
	ds_read_b128 v[130:133], v208
	ds_read_b128 v[134:137], v208 offset:1024
	ds_read_b128 v[138:141], v208 offset:2048
	ds_read_b128 v[142:145], v208 offset:3072
	ds_read_b128 v[146:149], v209
	ds_read_b128 v[150:153], v209 offset:1024
	ds_read_b128 v[154:157], v209 offset:2048
	ds_read_b128 v[158:161], v209 offset:3072
	s_add_u32 s18, s48, 0xfff80080
	s_addc_u32 s19, s49, -1
	s_cmp_eq_u32 s78, 28
	s_cselect_b32 s53, s41, s19
	s_cselect_b32 s52, s47, s18
	s_cselect_b32 s51, s39, s77
	s_cselect_b32 s50, s75, s76
	s_add_i32 m0, s62, 0xc000
	ds_read_b128 v[162:165], v210
	ds_read_b128 v[166:169], v210 offset:1024
	ds_read_b128 v[170:173], v210 offset:2048
	ds_read_b128 v[174:177], v210 offset:3072
	ds_read_b128 v[194:197], v210 offset:4096
	ds_read_b128 v[198:201], v210 offset:5120
	ds_read_b128 v[202:205], v210 offset:6144
	ds_read_b128 v[212:215], v210 offset:7168
	global_load_lds_dwordx4 v186, s[48:49]
	s_add_i32 m0, s62, 0xe000
	s_nop 0
	global_load_lds_dwordx4 v188, s[48:49]
	s_waitcnt vmcnt(8)
	s_waitcnt lgkmcnt(0)
	s_barrier
	s_waitcnt lgkmcnt(0)
	v_mfma_f32_16x16x32_bf16 v[126:129], v[130:133], v[162:165], 0
	v_mfma_f32_16x16x32_bf16 v[122:125], v[138:141], v[162:165], 0
	v_mfma_f32_16x16x32_bf16 v[110:113], v[130:133], v[170:173], 0
	v_mfma_f32_16x16x32_bf16 v[106:109], v[138:141], v[170:173], 0
	v_mfma_f32_16x16x32_bf16 v[94:97], v[130:133], v[194:197], 0
	v_mfma_f32_16x16x32_bf16 v[90:93], v[138:141], v[194:197], 0
	v_mfma_f32_16x16x32_bf16 v[78:81], v[130:133], v[202:205], 0
	v_mfma_f32_16x16x32_bf16 v[74:77], v[138:141], v[202:205], 0
	v_mfma_f32_16x16x32_bf16 v[126:129], v[134:137], v[166:169], v[126:129]
	v_mfma_f32_16x16x32_bf16 v[122:125], v[142:145], v[166:169], v[122:125]
	v_mfma_f32_16x16x32_bf16 v[110:113], v[134:137], v[174:177], v[110:113]
	v_mfma_f32_16x16x32_bf16 v[106:109], v[142:145], v[174:177], v[106:109]
	v_mfma_f32_16x16x32_bf16 v[94:97], v[134:137], v[198:201], v[94:97]
	v_mfma_f32_16x16x32_bf16 v[90:93], v[142:145], v[198:201], v[90:93]
	v_mfma_f32_16x16x32_bf16 v[78:81], v[134:137], v[212:215], v[78:81]
	v_mfma_f32_16x16x32_bf16 v[74:77], v[142:145], v[212:215], v[74:77]
	v_mfma_f32_16x16x32_bf16 v[118:121], v[146:149], v[162:165], 0
	v_mfma_f32_16x16x32_bf16 v[114:117], v[154:157], v[162:165], 0
	v_mfma_f32_16x16x32_bf16 v[102:105], v[146:149], v[170:173], 0
	v_mfma_f32_16x16x32_bf16 v[98:101], v[154:157], v[170:173], 0
	v_mfma_f32_16x16x32_bf16 v[86:89], v[146:149], v[194:197], 0
	v_mfma_f32_16x16x32_bf16 v[82:85], v[154:157], v[194:197], 0
	v_mfma_f32_16x16x32_bf16 v[70:73], v[146:149], v[202:205], 0
	v_mfma_f32_16x16x32_bf16 v[66:69], v[154:157], v[202:205], 0
	v_mfma_f32_16x16x32_bf16 v[118:121], v[150:153], v[166:169], v[118:121]
	v_mfma_f32_16x16x32_bf16 v[114:117], v[158:161], v[166:169], v[114:117]
	v_mfma_f32_16x16x32_bf16 v[102:105], v[150:153], v[174:177], v[102:105]
	v_mfma_f32_16x16x32_bf16 v[98:101], v[158:161], v[174:177], v[98:101]
	v_mfma_f32_16x16x32_bf16 v[86:89], v[150:153], v[198:201], v[86:89]
	v_mfma_f32_16x16x32_bf16 v[82:85], v[158:161], v[198:201], v[82:85]
	v_mfma_f32_16x16x32_bf16 v[70:73], v[150:153], v[212:215], v[70:73]
	v_mfma_f32_16x16x32_bf16 v[66:69], v[158:161], v[212:215], v[66:69]
	s_barrier
	s_add_i32 s18, s72, s61
	s_add_u32 s82, s50, s22
	s_addc_u32 s83, s51, s23
	s_mov_b32 m0, s18
	ds_read_b128 v[162:165], v210 offset:16384
	ds_read_b128 v[166:169], v210 offset:17408
	ds_read_b128 v[170:173], v210 offset:18432
	ds_read_b128 v[174:177], v210 offset:19456
	ds_read_b128 v[194:197], v210 offset:20480
	ds_read_b128 v[198:201], v210 offset:21504
	ds_read_b128 v[202:205], v210 offset:22528
	ds_read_b128 v[212:215], v210 offset:23552
	global_load_lds_dwordx4 v180, s[50:51]
	s_add_i32 m0, s18, 0x2000
	s_add_u32 s80, s50, 0x80000
	s_addc_u32 s81, s51, 0
	s_add_i32 s18, s73, s61
	global_load_lds_dwordx4 v184, s[50:51]
	s_mov_b32 m0, s18
	s_nop 0
	global_load_lds_dwordx4 v180, s[80:81]
	s_add_i32 m0, s18, 0x2000
	s_nop 0
	global_load_lds_dwordx4 v184, s[80:81]
	s_add_u32 s88, s52, s22
	s_addc_u32 s89, s53, s23
	s_mov_b32 m0, s62
	s_nop 0
	global_load_lds_dwordx4 v178, s[52:53]
	s_mov_b32 m0, s63
	s_nop 0
	global_load_lds_dwordx4 v182, s[52:53]
	s_waitcnt vmcnt(8)
	s_waitcnt lgkmcnt(0)
	s_barrier
; #define PG8_STAGE(bufoff, gbase, voff) do { _Pragma("unroll") for (int _i = 0; _i < 2; ++_i) \
;         __builtin_amdgcn_global_load_lds((const unsigned*)((const char*)(gbase) + (voff)[_i]), (PG8_LAS unsigned*)(lds + (bufoff) + ldsw + _i * 8192), 16, 0, 0); } while (0)
; #define PG8_LDA(dst, b, h) do { _Pragma("unroll") for (int m = 0; m < 4; ++m) _Pragma("unroll") for (int k = 0; k < 2; ++k) dst[m][k] = *(const PG8_LAS bf16x8*)(lds + PG8_SA(b, h) + aoff + m * 2048 + k * 1024); } while (0)
; #define PG8_LDB(dst, b, h) do { _Pragma("unroll") for (int n = 0; n < 2; ++n) _Pragma("unroll") for (int k = 0; k < 2; ++k) dst[n][k] = *(const PG8_LAS bf16x8*)(lds + PG8_SB(b, h) + boff + n * 2048 + k * 1024); } while (0)
; #define PG8_MMA(ai, bj, At, Bt) do { __builtin_amdgcn_s_setprio(1); _Pragma("unroll") for (int m = 0; m < 4; ++m) _Pragma("unroll") for (int n = 0; n < 2; ++n) _Pragma("unroll") for (int k = 0; k < 2; ++k) \
;         acc[ai][bj][m][n] = __builtin_amdgcn_mfma_f32_16x16x32_bf16(Bt[n][k], At[m][k], acc[ai][bj][m][n], 0, 0, 0); __builtin_amdgcn_s_setprio(0); } while (0)
; #define PG8_WAIT_V(n) asm volatile("s_waitcnt vmcnt(" #n ")" ::: "memory")
; #define PG8_WAIT_L(n) asm volatile("s_waitcnt lgkmcnt(" #n ")" ::: "memory")
; #define PG8_BAR __builtin_amdgcn_s_barrier()
; #define PG8_SCHED __builtin_amdgcn_sched_barrier(0)
; template <class Epi, class Sched, bool ALIGN_EPI = false, bool SP2 = false>
; __device__ __forceinline__ void gemm_phase(PG8_LAS unsigned char* lds, const Gemm g, const Sched& S, const Epi& E) {
;     ...
;             PG8_WAIT_V(8); PG8_WAIT_L(0); PG8_BAR; PG8_MMA(0, 0, At, B0); PG8_MMA(0, 1, At, B1); PG8_BAR; PG8_SCHED;
;             PG8_LDA(At, 0, 1); PG8_STAGE(PG8_SB(0, 0), b2, voffB); PG8_STAGE(PG8_SB(0, 1), b2 + hB, voffB); PG8_STAGE(PG8_SA(0, 0), a2, voffA);
;             PG8_WAIT_V(8); PG8_WAIT_L(0); PG8_BAR; PG8_MMA(1, 0, At, B0); PG8_MMA(1, 1, At, B1); PG8_BAR; PG8_SCHED;
;             PG8_LDB(B0, 1, 0); PG8_LDB(B1, 1, 1); PG8_SCHED; PG8_LDA(At, 1, 0); PG8_STAGE(PG8_SA(0, 1), a2 + hA, voffA);
;             PG8_WAIT_V(8); PG8_WAIT_L(0); PG8_BAR; PG8_MMA(0, 0, At, B0); PG8_MMA(0, 1, At, B1); PG8_BAR; PG8_SCHED;
	s_waitcnt lgkmcnt(0)
	v_mfma_f32_16x16x32_bf16 v[62:65], v[130:133], v[162:165], 0
	v_mfma_f32_16x16x32_bf16 v[58:61], v[138:141], v[162:165], 0
	v_mfma_f32_16x16x32_bf16 v[46:49], v[130:133], v[170:173], 0
	v_mfma_f32_16x16x32_bf16 v[42:45], v[138:141], v[170:173], 0
	v_mfma_f32_16x16x32_bf16 v[30:33], v[130:133], v[194:197], 0
	v_mfma_f32_16x16x32_bf16 v[26:29], v[138:141], v[194:197], 0
	v_mfma_f32_16x16x32_bf16 v[14:17], v[130:133], v[202:205], 0
	v_mfma_f32_16x16x32_bf16 v[10:13], v[138:141], v[202:205], 0
	v_mfma_f32_16x16x32_bf16 v[62:65], v[134:137], v[166:169], v[62:65]
	v_mfma_f32_16x16x32_bf16 v[58:61], v[142:145], v[166:169], v[58:61]
	v_mfma_f32_16x16x32_bf16 v[46:49], v[134:137], v[174:177], v[46:49]
	v_mfma_f32_16x16x32_bf16 v[42:45], v[142:145], v[174:177], v[42:45]
	v_mfma_f32_16x16x32_bf16 v[30:33], v[134:137], v[198:201], v[30:33]
	v_mfma_f32_16x16x32_bf16 v[26:29], v[142:145], v[198:201], v[26:29]
	v_mfma_f32_16x16x32_bf16 v[14:17], v[134:137], v[212:215], v[14:17]
	v_mfma_f32_16x16x32_bf16 v[10:13], v[142:145], v[212:215], v[10:13]
	v_mfma_f32_16x16x32_bf16 v[54:57], v[146:149], v[162:165], 0
	v_mfma_f32_16x16x32_bf16 v[50:53], v[154:157], v[162:165], 0
	v_mfma_f32_16x16x32_bf16 v[38:41], v[146:149], v[170:173], 0
	v_mfma_f32_16x16x32_bf16 v[34:37], v[154:157], v[170:173], 0
	v_mfma_f32_16x16x32_bf16 v[22:25], v[146:149], v[194:197], 0
	v_mfma_f32_16x16x32_bf16 v[18:21], v[154:157], v[194:197], 0
	v_mfma_f32_16x16x32_bf16 v[6:9], v[146:149], v[202:205], 0
	v_mfma_f32_16x16x32_bf16 v[2:5], v[154:157], v[202:205], 0
	v_mfma_f32_16x16x32_bf16 v[54:57], v[150:153], v[166:169], v[54:57]
	v_mfma_f32_16x16x32_bf16 v[50:53], v[158:161], v[166:169], v[50:53]
	v_mfma_f32_16x16x32_bf16 v[38:41], v[150:153], v[174:177], v[38:41]
	v_mfma_f32_16x16x32_bf16 v[34:37], v[158:161], v[174:177], v[34:37]
	v_mfma_f32_16x16x32_bf16 v[22:25], v[150:153], v[198:201], v[22:25]
	v_mfma_f32_16x16x32_bf16 v[18:21], v[158:161], v[198:201], v[18:21]
	v_mfma_f32_16x16x32_bf16 v[6:9], v[150:153], v[212:215], v[6:9]
	v_mfma_f32_16x16x32_bf16 v[2:5], v[158:161], v[212:215], v[2:5]
	s_barrier
	s_add_i32 s18, 0, 0x18000
	s_add_i32 s19, 0, 0x1c000
	v_add_u32_e32 v142, s18, v206
	v_add_u32_e32 v158, s19, v206
	ds_read_b128 v[130:133], v142
	ds_read_b128 v[134:137], v142 offset:1024
	ds_read_b128 v[138:141], v142 offset:2048
	ds_read_b128 v[142:145], v142 offset:3072
	ds_read_b128 v[146:149], v158
	ds_read_b128 v[150:153], v158 offset:1024
	ds_read_b128 v[154:157], v158 offset:2048
	ds_read_b128 v[158:161], v158 offset:3072
	s_add_u32 s52, s52, 0x80000
	s_addc_u32 s53, s53, 0
	s_mov_b32 m0, s64
	ds_read_b128 v[162:165], v210 offset:32768
	ds_read_b128 v[166:169], v210 offset:33792
	ds_read_b128 v[170:173], v210 offset:34816
	ds_read_b128 v[174:177], v210 offset:35840
	ds_read_b128 v[194:197], v210 offset:36864
	ds_read_b128 v[198:201], v210 offset:37888
	ds_read_b128 v[202:205], v210 offset:38912
	ds_read_b128 v[212:215], v210 offset:39936
	global_load_lds_dwordx4 v178, s[52:53]
	s_mov_b32 m0, s65
	s_nop 0
	global_load_lds_dwordx4 v182, s[52:53]
	s_waitcnt vmcnt(8)
	s_waitcnt lgkmcnt(0)
	s_barrier
	s_waitcnt lgkmcnt(0)
	v_mfma_f32_16x16x32_bf16 v[126:129], v[130:133], v[162:165], v[126:129]
	v_mfma_f32_16x16x32_bf16 v[122:125], v[138:141], v[162:165], v[122:125]
	v_mfma_f32_16x16x32_bf16 v[110:113], v[130:133], v[170:173], v[110:113]
	v_mfma_f32_16x16x32_bf16 v[106:109], v[138:141], v[170:173], v[106:109]
	v_mfma_f32_16x16x32_bf16 v[94:97], v[130:133], v[194:197], v[94:97]
	v_mfma_f32_16x16x32_bf16 v[90:93], v[138:141], v[194:197], v[90:93]
	v_mfma_f32_16x16x32_bf16 v[78:81], v[130:133], v[202:205], v[78:81]
	v_mfma_f32_16x16x32_bf16 v[74:77], v[138:141], v[202:205], v[74:77]
	v_mfma_f32_16x16x32_bf16 v[126:129], v[134:137], v[166:169], v[126:129]
	v_mfma_f32_16x16x32_bf16 v[122:125], v[142:145], v[166:169], v[122:125]
	v_mfma_f32_16x16x32_bf16 v[110:113], v[134:137], v[174:177], v[110:113]
	v_mfma_f32_16x16x32_bf16 v[106:109], v[142:145], v[174:177], v[106:109]
	v_mfma_f32_16x16x32_bf16 v[94:97], v[134:137], v[198:201], v[94:97]
	v_mfma_f32_16x16x32_bf16 v[90:93], v[142:145], v[198:201], v[90:93]
	v_mfma_f32_16x16x32_bf16 v[78:81], v[134:137], v[212:215], v[78:81]
	v_mfma_f32_16x16x32_bf16 v[74:77], v[142:145], v[212:215], v[74:77]
	v_mfma_f32_16x16x32_bf16 v[118:121], v[146:149], v[162:165], v[118:121]
	v_mfma_f32_16x16x32_bf16 v[114:117], v[154:157], v[162:165], v[114:117]
	v_mfma_f32_16x16x32_bf16 v[102:105], v[146:149], v[170:173], v[102:105]
	v_mfma_f32_16x16x32_bf16 v[98:101], v[154:157], v[170:173], v[98:101]
	v_mfma_f32_16x16x32_bf16 v[86:89], v[146:149], v[194:197], v[86:89]
	v_mfma_f32_16x16x32_bf16 v[82:85], v[154:157], v[194:197], v[82:85]
	v_mfma_f32_16x16x32_bf16 v[70:73], v[146:149], v[202:205], v[70:73]
	v_mfma_f32_16x16x32_bf16 v[66:69], v[154:157], v[202:205], v[66:69]
	v_mfma_f32_16x16x32_bf16 v[118:121], v[150:153], v[166:169], v[118:121]
	v_mfma_f32_16x16x32_bf16 v[114:117], v[158:161], v[166:169], v[114:117]
	v_mfma_f32_16x16x32_bf16 v[102:105], v[150:153], v[174:177], v[102:105]
	v_mfma_f32_16x16x32_bf16 v[98:101], v[158:161], v[174:177], v[98:101]
	v_mfma_f32_16x16x32_bf16 v[86:89], v[150:153], v[198:201], v[86:89]
	v_mfma_f32_16x16x32_bf16 v[82:85], v[158:161], v[198:201], v[82:85]
	v_mfma_f32_16x16x32_bf16 v[70:73], v[150:153], v[212:215], v[70:73]
	v_mfma_f32_16x16x32_bf16 v[66:69], v[158:161], v[212:215], v[66:69]
	s_barrier
; #define PG8_STAGE(bufoff, gbase, voff) do { _Pragma("unroll") for (int _i = 0; _i < 2; ++_i) \
;         __builtin_amdgcn_global_load_lds((const unsigned*)((const char*)(gbase) + (voff)[_i]), (PG8_LAS unsigned*)(lds + (bufoff) + ldsw + _i * 8192), 16, 0, 0); } while (0)
; #define PG8_LDA(dst, b, h) do { _Pragma("unroll") for (int m = 0; m < 4; ++m) _Pragma("unroll") for (int k = 0; k < 2; ++k) dst[m][k] = *(const PG8_LAS bf16x8*)(lds + PG8_SA(b, h) + aoff + m * 2048 + k * 1024); } while (0)
; #define PG8_MMA(ai, bj, At, Bt) do { __builtin_amdgcn_s_setprio(1); _Pragma("unroll") for (int m = 0; m < 4; ++m) _Pragma("unroll") for (int n = 0; n < 2; ++n) _Pragma("unroll") for (int k = 0; k < 2; ++k) \
;         acc[ai][bj][m][n] = __builtin_amdgcn_mfma_f32_16x16x32_bf16(Bt[n][k], At[m][k], acc[ai][bj][m][n], 0, 0, 0); __builtin_amdgcn_s_setprio(0); } while (0)
; #define PG8_WAIT_V(n) asm volatile("s_waitcnt vmcnt(" #n ")" ::: "memory")
; #define PG8_WAIT_L(n) asm volatile("s_waitcnt lgkmcnt(" #n ")" ::: "memory")
; #define PG8_BAR __builtin_amdgcn_s_barrier()
; #define PG8_SCHED __builtin_amdgcn_sched_barrier(0)
; template <class Epi, class Sched, bool ALIGN_EPI = false, bool SP2 = false>
; __device__ __forceinline__ void gemm_phase(PG8_LAS unsigned char* lds, const Gemm g, const Sched& S, const Epi& E) {
;     ...
;         for (int t = 0; t < nt; t += 2) {
;             const bool last = (t == nt - 2);
;             const char* a1 = cA + (size_t)(t + 1) * kstep;
;             const char* a2 = last ? nA : cA + (size_t)(t + 2) * kstep; const char* b2 = last ? nB : cB + (size_t)(t + 2) * kstep;
;     ...
;             PG8_LDA(At, 1, 1); PG8_STAGE(PG8_SB(1, 0), b3, voffB); PG8_STAGE(PG8_SB(1, 1), b3 + hB, voffB); PG8_STAGE(PG8_SA(1, 0), a3, voffA);
;             PG8_WAIT_V(8); PG8_WAIT_L(0); PG8_BAR; PG8_MMA(1, 0, At, B0); PG8_MMA(1, 1, At, B1); PG8_BAR; PG8_SCHED;
	s_add_i32 s18, s18, s61
	s_mov_b32 m0, s18
	ds_read_b128 v[162:165], v210 offset:49152
	ds_read_b128 v[166:169], v210 offset:50176
	ds_read_b128 v[170:173], v210 offset:51200
	ds_read_b128 v[174:177], v210 offset:52224
	ds_read_b128 v[194:197], v210 offset:53248
	ds_read_b128 v[198:201], v210 offset:54272
	ds_read_b128 v[202:205], v210 offset:55296
	ds_read_b128 v[212:215], v210 offset:56320
	global_load_lds_dwordx4 v180, s[82:83]
	s_add_i32 m0, s18, 0x2000
	s_add_u32 s50, s50, 0x80080
	s_addc_u32 s51, s51, 0
	s_add_i32 s18, s19, s61
	global_load_lds_dwordx4 v184, s[82:83]
	s_mov_b32 m0, s18
	s_nop 0
	global_load_lds_dwordx4 v180, s[50:51]
	s_add_i32 m0, s18, 0x2000
	s_nop 0
	global_load_lds_dwordx4 v184, s[50:51]
	s_mov_b32 m0, s69
	s_nop 0
	global_load_lds_dwordx4 v178, s[88:89]
	s_mov_b32 m0, s70
	s_nop 0
	global_load_lds_dwordx4 v182, s[88:89]
	s_waitcnt vmcnt(8)
	s_waitcnt lgkmcnt(0)
	s_barrier
	s_waitcnt lgkmcnt(0)
	v_mfma_f32_16x16x32_bf16 v[62:65], v[130:133], v[162:165], v[62:65]
	v_mfma_f32_16x16x32_bf16 v[58:61], v[138:141], v[162:165], v[58:61]
	v_mfma_f32_16x16x32_bf16 v[46:49], v[130:133], v[170:173], v[46:49]
	v_mfma_f32_16x16x32_bf16 v[42:45], v[138:141], v[170:173], v[42:45]
	v_mfma_f32_16x16x32_bf16 v[30:33], v[130:133], v[194:197], v[30:33]
	v_mfma_f32_16x16x32_bf16 v[26:29], v[138:141], v[194:197], v[26:29]
	v_mfma_f32_16x16x32_bf16 v[14:17], v[130:133], v[202:205], v[14:17]
	v_mfma_f32_16x16x32_bf16 v[10:13], v[138:141], v[202:205], v[10:13]
	v_mfma_f32_16x16x32_bf16 v[62:65], v[134:137], v[166:169], v[62:65]
	v_mfma_f32_16x16x32_bf16 v[58:61], v[142:145], v[166:169], v[58:61]
	v_mfma_f32_16x16x32_bf16 v[46:49], v[134:137], v[174:177], v[46:49]
	v_mfma_f32_16x16x32_bf16 v[42:45], v[142:145], v[174:177], v[42:45]
	v_mfma_f32_16x16x32_bf16 v[30:33], v[134:137], v[198:201], v[30:33]
	v_mfma_f32_16x16x32_bf16 v[26:29], v[142:145], v[198:201], v[26:29]
	v_mfma_f32_16x16x32_bf16 v[14:17], v[134:137], v[212:215], v[14:17]
	v_mfma_f32_16x16x32_bf16 v[10:13], v[142:145], v[212:215], v[10:13]
	v_mfma_f32_16x16x32_bf16 v[54:57], v[146:149], v[162:165], v[54:57]
	v_mfma_f32_16x16x32_bf16 v[50:53], v[154:157], v[162:165], v[50:53]
	v_mfma_f32_16x16x32_bf16 v[38:41], v[146:149], v[170:173], v[38:41]
	v_mfma_f32_16x16x32_bf16 v[34:37], v[154:157], v[170:173], v[34:37]
	v_mfma_f32_16x16x32_bf16 v[22:25], v[146:149], v[194:197], v[22:25]
	v_mfma_f32_16x16x32_bf16 v[18:21], v[154:157], v[194:197], v[18:21]
	v_mfma_f32_16x16x32_bf16 v[6:9], v[146:149], v[202:205], v[6:9]
	v_mfma_f32_16x16x32_bf16 v[2:5], v[154:157], v[202:205], v[2:5]
	v_mfma_f32_16x16x32_bf16 v[54:57], v[150:153], v[166:169], v[54:57]
	v_mfma_f32_16x16x32_bf16 v[50:53], v[158:161], v[166:169], v[50:53]
	v_mfma_f32_16x16x32_bf16 v[38:41], v[150:153], v[174:177], v[38:41]
	v_mfma_f32_16x16x32_bf16 v[34:37], v[158:161], v[174:177], v[34:37]
	v_mfma_f32_16x16x32_bf16 v[22:25], v[150:153], v[198:201], v[22:25]
	v_mfma_f32_16x16x32_bf16 v[18:21], v[158:161], v[198:201], v[18:21]
	v_mfma_f32_16x16x32_bf16 v[6:9], v[150:153], v[212:215], v[6:9]
	v_mfma_f32_16x16x32_bf16 v[2:5], v[158:161], v[212:215], v[2:5]
	s_barrier
	s_add_i32 s78, s78, 2
	s_add_u32 s48, s48, 0x100
	s_addc_u32 s49, s49, 0
	s_add_u32 s76, s76, 0x100
	s_addc_u32 s77, s77, 0
	s_cmp_gt_u32 s78, 29

; #define PG8_STAGE(bufoff, gbase, voff) do { _Pragma("unroll") for (int _i = 0; _i < 2; ++_i) \
;         __builtin_amdgcn_global_load_lds((const unsigned*)((const char*)(gbase) + (voff)[_i]), (PG8_LAS unsigned*)(lds + (bufoff) + ldsw + _i * 8192), 16, 0, 0); } while (0)
; #define PG8_LDA(dst, b, h) do { _Pragma("unroll") for (int m = 0; m < 4; ++m) _Pragma("unroll") for (int k = 0; k < 2; ++k) dst[m][k] = *(const PG8_LAS bf16x8*)(lds + PG8_SA(b, h) + aoff + m * 2048 + k * 1024); } while (0)
; #define PG8_WAIT_V(n) asm volatile("s_waitcnt vmcnt(" #n ")" ::: "memory")
; #define PG8_WAIT_L(n) asm volatile("s_waitcnt lgkmcnt(" #n ")" ::: "memory")
; #define PG8_BAR __builtin_amdgcn_s_barrier()
; template <class Epi, class Sched, bool ALIGN_EPI = false, bool SP2 = false>
; __device__ __forceinline__ void gemm_phase(PG8_LAS unsigned char* lds, const Gemm g, const Sched& S, const Epi& E) {
;     ...
;         const bool has_next = S.next(ui + 1, nxt);
;         const char* nA = has_next ? (const char*)g.A + (size_t)nxt.pm * tA + (size_t)nxt.pn * pnA : cA; const char* nB = has_next ? (const char*)g.Bt + (size_t)nxt.pn * tB : cB;
; #pragma nounroll
;         for (int t = 0; t < nt; t += 2) {
;             const bool last = (t == nt - 2);
;             const char* a1 = cA + (size_t)(t + 1) * kstep;
;             const char* a2 = last ? nA : cA + (size_t)(t + 2) * kstep; const char* b2 = last ? nB : cB + (size_t)(t + 2) * kstep;
;             const char* a3 = a2 + kstep; const char* b3 = b2 + kstep;
;             if (last && has_next) S.a_ready(nxt);
;             if constexpr (SP2) {
;             PG8_LDB(B0, 0, 0); PG8_LDB(B1, 0, 1); PG8_SCHED; PG8_LDA(At, 0, 0); PG8_STAGE(PG8_SA(1, 1), a1 + hA, voffA);
;             PG8_WAIT_V(8); PG8_WAIT_L(0); PG8_BAR; PG8_MMA(0, 0, At, B0); PG8_MMA(0, 1, At, B1); PG8_BAR; PG8_SCHED;
;             PG8_LDA(At, 0, 1); PG8_STAGE(PG8_SB(0, 0), b2, voffB); PG8_STAGE(PG8_SB(0, 1), b2 + hB, voffB); PG8_STAGE(PG8_SA(0, 0), a2, voffA);
;             PG8_WAIT_V(8); PG8_WAIT_L(0); PG8_BAR; PG8_MMA(1, 0, At, B0); PG8_MMA(1, 1, At, B1); PG8_BAR; PG8_SCHED;
;     ...
; #pragma unroll
;         for (int a = 0; a < 2; ++a)
; #pragma unroll
;             for (int b = 0; b < 2; ++b)
; #pragma unroll
;                 for (int m = 0; m < 4; ++m)
; #pragma unroll
;                     for (int n = 0; n < 2; ++n) acc[a][b][m][n] = (f32x4){0.f, 0.f, 0.f, 0.f};
.LBB0_1047:
	s_ashr_i32 s37, s36, 31
	s_lshl_b64 s[38:39], s[36:37], 20
	s_add_u32 s38, s33, s38
	s_addc_u32 s39, s46, s39
	s_and_b64 s[40:41], s[6:7], exec
	s_cselect_b32 s1, s39, s9
	s_cselect_b32 s37, s38, s8
	s_ashr_i32 s25, s24, 31
	s_lshl_b64 s[40:41], s[24:25], 20
	s_add_u32 s40, s47, s40
	s_addc_u32 s41, s48, s41
	s_and_b64 s[44:45], s[6:7], exec
	s_cselect_b32 s25, s41, s43
	s_cselect_b32 s69, s40, s42
	s_add_u32 s8, s8, 0x80080
	s_addc_u32 s9, s9, 0
	s_add_u32 s70, s42, 0x100
	v_mov_b32_e32 v2, 0
	s_addc_u32 s71, s43, 0
	s_mov_b32 s72, -2
	v_mov_b32_e32 v3, v2
	ds_read_b128 v[148:151], v169
	ds_read_b128 v[152:155], v169 offset:1024
	ds_read_b128 v[156:159], v169 offset:2048
	ds_read_b128 v[160:163], v169 offset:3072
	ds_read_b128 v[180:183], v171
	ds_read_b128 v[184:187], v171 offset:1024
	ds_read_b128 v[188:191], v171 offset:2048
	ds_read_b128 v[192:195], v171 offset:3072
	s_add_u32 s18, s8, 0xfff80080
	s_addc_u32 s19, s9, -1
	s_cmp_eq_u32 s72, 28
	s_cselect_b32 s45, s1, s19
	s_cselect_b32 s44, s37, s18
	s_cselect_b32 s43, s25, s71
	s_cselect_b32 s42, s69, s70
	s_add_i32 m0, s51, 0xc000
	ds_read_b128 v[196:199], v173
	ds_read_b128 v[200:203], v173 offset:1024
	ds_read_b128 v[204:207], v173 offset:2048
	ds_read_b128 v[208:211], v173 offset:3072
	ds_read_b128 v[212:215], v173 offset:4096
	ds_read_b128 v[216:219], v173 offset:5120
	ds_read_b128 v[224:227], v173 offset:6144
	ds_read_b128 v[228:231], v173 offset:7168
	global_load_lds_dwordx4 v140, s[8:9]
	s_add_i32 m0, s51, 0xe000
	s_nop 0
	global_load_lds_dwordx4 v142, s[8:9]
	s_waitcnt vmcnt(8)
	s_waitcnt lgkmcnt(0)
	s_barrier
	s_waitcnt lgkmcnt(0)
	v_mfma_f32_16x16x32_bf16 v[126:129], v[148:151], v[196:199], 0
	v_mfma_f32_16x16x32_bf16 v[122:125], v[156:159], v[196:199], 0
	v_mfma_f32_16x16x32_bf16 v[110:113], v[148:151], v[204:207], 0
	v_mfma_f32_16x16x32_bf16 v[106:109], v[156:159], v[204:207], 0
	v_mfma_f32_16x16x32_bf16 v[94:97], v[148:151], v[212:215], 0
	v_mfma_f32_16x16x32_bf16 v[90:93], v[156:159], v[212:215], 0
	v_mfma_f32_16x16x32_bf16 v[78:81], v[148:151], v[224:227], 0
	v_mfma_f32_16x16x32_bf16 v[74:77], v[156:159], v[224:227], 0
	v_mfma_f32_16x16x32_bf16 v[126:129], v[152:155], v[200:203], v[126:129]
	v_mfma_f32_16x16x32_bf16 v[122:125], v[160:163], v[200:203], v[122:125]
	v_mfma_f32_16x16x32_bf16 v[110:113], v[152:155], v[208:211], v[110:113]
	v_mfma_f32_16x16x32_bf16 v[106:109], v[160:163], v[208:211], v[106:109]
	v_mfma_f32_16x16x32_bf16 v[94:97], v[152:155], v[216:219], v[94:97]
	v_mfma_f32_16x16x32_bf16 v[90:93], v[160:163], v[216:219], v[90:93]
	v_mfma_f32_16x16x32_bf16 v[78:81], v[152:155], v[228:231], v[78:81]
	v_mfma_f32_16x16x32_bf16 v[74:77], v[160:163], v[228:231], v[74:77]
	v_mfma_f32_16x16x32_bf16 v[118:121], v[180:183], v[196:199], 0
	v_mfma_f32_16x16x32_bf16 v[114:117], v[188:191], v[196:199], 0
	v_mfma_f32_16x16x32_bf16 v[102:105], v[180:183], v[204:207], 0
	v_mfma_f32_16x16x32_bf16 v[98:101], v[188:191], v[204:207], 0
	v_mfma_f32_16x16x32_bf16 v[86:89], v[180:183], v[212:215], 0
	v_mfma_f32_16x16x32_bf16 v[82:85], v[188:191], v[212:215], 0
	v_mfma_f32_16x16x32_bf16 v[70:73], v[180:183], v[224:227], 0
	v_mfma_f32_16x16x32_bf16 v[66:69], v[188:191], v[224:227], 0
	v_mfma_f32_16x16x32_bf16 v[118:121], v[184:187], v[200:203], v[118:121]
	v_mfma_f32_16x16x32_bf16 v[114:117], v[192:195], v[200:203], v[114:117]
	v_mfma_f32_16x16x32_bf16 v[102:105], v[184:187], v[208:211], v[102:105]
	v_mfma_f32_16x16x32_bf16 v[98:101], v[192:195], v[208:211], v[98:101]
	v_mfma_f32_16x16x32_bf16 v[86:89], v[184:187], v[216:219], v[86:89]
	v_mfma_f32_16x16x32_bf16 v[82:85], v[192:195], v[216:219], v[82:85]
	v_mfma_f32_16x16x32_bf16 v[70:73], v[184:187], v[228:231], v[70:73]
	v_mfma_f32_16x16x32_bf16 v[66:69], v[192:195], v[228:231], v[66:69]
	s_barrier
	s_add_i32 s18, s63, s49
	s_add_u32 s76, s42, s20
	s_addc_u32 s77, s43, s21
	s_mov_b32 m0, s18
	ds_read_b128 v[196:199], v173 offset:16384
	ds_read_b128 v[200:203], v173 offset:17408
	ds_read_b128 v[204:207], v173 offset:18432
	ds_read_b128 v[208:211], v173 offset:19456
	ds_read_b128 v[212:215], v173 offset:20480
	ds_read_b128 v[216:219], v173 offset:21504
	ds_read_b128 v[224:227], v173 offset:22528
	ds_read_b128 v[228:231], v173 offset:23552
	global_load_lds_dwordx4 v134, s[42:43]
	s_add_i32 m0, s18, 0x2000
	s_add_u32 s74, s42, 0x80000
	s_addc_u32 s75, s43, 0
	s_add_i32 s18, s64, s49
	global_load_lds_dwordx4 v130, s[42:43]
	s_mov_b32 m0, s18
	s_nop 0
	global_load_lds_dwordx4 v134, s[74:75]
	s_add_i32 m0, s18, 0x2000
	s_nop 0
	global_load_lds_dwordx4 v130, s[74:75]
	s_add_u32 s78, s44, s20
	s_addc_u32 s79, s45, s21
	s_mov_b32 m0, s51
	s_nop 0
	global_load_lds_dwordx4 v136, s[44:45]
	s_mov_b32 m0, s52
	s_nop 0
	global_load_lds_dwordx4 v132, s[44:45]
	s_waitcnt vmcnt(8)
	s_waitcnt lgkmcnt(0)
	s_barrier
; #define PG8_STAGE(bufoff, gbase, voff) do { _Pragma("unroll") for (int _i = 0; _i < 2; ++_i) \
;         __builtin_amdgcn_global_load_lds((const unsigned*)((const char*)(gbase) + (voff)[_i]), (PG8_LAS unsigned*)(lds + (bufoff) + ldsw + _i * 8192), 16, 0, 0); } while (0)
; #define PG8_LDA(dst, b, h) do { _Pragma("unroll") for (int m = 0; m < 4; ++m) _Pragma("unroll") for (int k = 0; k < 2; ++k) dst[m][k] = *(const PG8_LAS bf16x8*)(lds + PG8_SA(b, h) + aoff + m * 2048 + k * 1024); } while (0)
; #define PG8_LDB(dst, b, h) do { _Pragma("unroll") for (int n = 0; n < 2; ++n) _Pragma("unroll") for (int k = 0; k < 2; ++k) dst[n][k] = *(const PG8_LAS bf16x8*)(lds + PG8_SB(b, h) + boff + n * 2048 + k * 1024); } while (0)
; #define PG8_MMA(ai, bj, At, Bt) do { __builtin_amdgcn_s_setprio(1); _Pragma("unroll") for (int m = 0; m < 4; ++m) _Pragma("unroll") for (int n = 0; n < 2; ++n) _Pragma("unroll") for (int k = 0; k < 2; ++k) \
;         acc[ai][bj][m][n] = __builtin_amdgcn_mfma_f32_16x16x32_bf16(Bt[n][k], At[m][k], acc[ai][bj][m][n], 0, 0, 0); __builtin_amdgcn_s_setprio(0); } while (0)
; #define PG8_WAIT_V(n) asm volatile("s_waitcnt vmcnt(" #n ")" ::: "memory")
; #define PG8_WAIT_L(n) asm volatile("s_waitcnt lgkmcnt(" #n ")" ::: "memory")
; #define PG8_BAR __builtin_amdgcn_s_barrier()
; #define PG8_SCHED __builtin_amdgcn_sched_barrier(0)
; template <class Epi, class Sched, bool ALIGN_EPI = false, bool SP2 = false>
; __device__ __forceinline__ void gemm_phase(PG8_LAS unsigned char* lds, const Gemm g, const Sched& S, const Epi& E) {
;     ...
;             PG8_WAIT_V(8); PG8_WAIT_L(0); PG8_BAR; PG8_MMA(0, 0, At, B0); PG8_MMA(0, 1, At, B1); PG8_BAR; PG8_SCHED;
;             PG8_LDA(At, 0, 1); PG8_STAGE(PG8_SB(0, 0), b2, voffB); PG8_STAGE(PG8_SB(0, 1), b2 + hB, voffB); PG8_STAGE(PG8_SA(0, 0), a2, voffA);
;             PG8_WAIT_V(8); PG8_WAIT_L(0); PG8_BAR; PG8_MMA(1, 0, At, B0); PG8_MMA(1, 1, At, B1); PG8_BAR; PG8_SCHED;
;             PG8_LDB(B0, 1, 0); PG8_LDB(B1, 1, 1); PG8_SCHED; PG8_LDA(At, 1, 0); PG8_STAGE(PG8_SA(0, 1), a2 + hA, voffA);
;             PG8_WAIT_V(8); PG8_WAIT_L(0); PG8_BAR; PG8_MMA(0, 0, At, B0); PG8_MMA(0, 1, At, B1); PG8_BAR; PG8_SCHED;
	s_waitcnt lgkmcnt(0)
	v_mfma_f32_16x16x32_bf16 v[62:65], v[148:151], v[196:199], 0
	v_mfma_f32_16x16x32_bf16 v[58:61], v[156:159], v[196:199], 0
	v_mfma_f32_16x16x32_bf16 v[46:49], v[148:151], v[204:207], 0
	v_mfma_f32_16x16x32_bf16 v[42:45], v[156:159], v[204:207], 0
	v_mfma_f32_16x16x32_bf16 v[30:33], v[148:151], v[212:215], 0
	v_mfma_f32_16x16x32_bf16 v[26:29], v[156:159], v[212:215], 0
	v_mfma_f32_16x16x32_bf16 v[14:17], v[148:151], v[224:227], 0
	v_mfma_f32_16x16x32_bf16 v[10:13], v[156:159], v[224:227], 0
	v_mfma_f32_16x16x32_bf16 v[62:65], v[152:155], v[200:203], v[62:65]
	v_mfma_f32_16x16x32_bf16 v[58:61], v[160:163], v[200:203], v[58:61]
	v_mfma_f32_16x16x32_bf16 v[46:49], v[152:155], v[208:211], v[46:49]
	v_mfma_f32_16x16x32_bf16 v[42:45], v[160:163], v[208:211], v[42:45]
	v_mfma_f32_16x16x32_bf16 v[30:33], v[152:155], v[216:219], v[30:33]
	v_mfma_f32_16x16x32_bf16 v[26:29], v[160:163], v[216:219], v[26:29]
	v_mfma_f32_16x16x32_bf16 v[14:17], v[152:155], v[228:231], v[14:17]
	v_mfma_f32_16x16x32_bf16 v[10:13], v[160:163], v[228:231], v[10:13]
	v_mfma_f32_16x16x32_bf16 v[54:57], v[180:183], v[196:199], 0
	v_mfma_f32_16x16x32_bf16 v[50:53], v[188:191], v[196:199], 0
	v_mfma_f32_16x16x32_bf16 v[38:41], v[180:183], v[204:207], 0
	v_mfma_f32_16x16x32_bf16 v[34:37], v[188:191], v[204:207], 0
	v_mfma_f32_16x16x32_bf16 v[22:25], v[180:183], v[212:215], 0
	v_mfma_f32_16x16x32_bf16 v[18:21], v[188:191], v[212:215], 0
	v_mfma_f32_16x16x32_bf16 v[6:9], v[180:183], v[224:227], 0
	v_mfma_f32_16x16x32_bf16 v[2:5], v[188:191], v[224:227], 0
	v_mfma_f32_16x16x32_bf16 v[54:57], v[184:187], v[200:203], v[54:57]
	v_mfma_f32_16x16x32_bf16 v[50:53], v[192:195], v[200:203], v[50:53]
	v_mfma_f32_16x16x32_bf16 v[38:41], v[184:187], v[208:211], v[38:41]
	v_mfma_f32_16x16x32_bf16 v[34:37], v[192:195], v[208:211], v[34:37]
	v_mfma_f32_16x16x32_bf16 v[22:25], v[184:187], v[216:219], v[22:25]
	v_mfma_f32_16x16x32_bf16 v[18:21], v[192:195], v[216:219], v[18:21]
	v_mfma_f32_16x16x32_bf16 v[6:9], v[184:187], v[228:231], v[6:9]
	v_mfma_f32_16x16x32_bf16 v[2:5], v[192:195], v[228:231], v[2:5]
	s_barrier
	s_add_i32 s18, 0, 0x18000
	s_add_i32 s19, 0, 0x1c000
	v_add_u32_e32 v160, s18, v165
	v_add_u32_e32 v164, s19, v165
	ds_read_b128 v[148:151], v160
	ds_read_b128 v[152:155], v160 offset:1024
	ds_read_b128 v[156:159], v160 offset:2048
	ds_read_b128 v[160:163], v160 offset:3072
	ds_read_b128 v[180:183], v164
	ds_read_b128 v[184:187], v164 offset:1024
	ds_read_b128 v[188:191], v164 offset:2048
	ds_read_b128 v[192:195], v164 offset:3072
	s_add_u32 s44, s44, 0x80000
	s_addc_u32 s45, s45, 0
	s_mov_b32 m0, s53
	ds_read_b128 v[196:199], v173 offset:32768
	ds_read_b128 v[200:203], v173 offset:33792
	ds_read_b128 v[204:207], v173 offset:34816
	ds_read_b128 v[208:211], v173 offset:35840
	ds_read_b128 v[212:215], v173 offset:36864
	ds_read_b128 v[216:219], v173 offset:37888
	ds_read_b128 v[224:227], v173 offset:38912
	ds_read_b128 v[228:231], v173 offset:39936
	global_load_lds_dwordx4 v136, s[44:45]
	s_mov_b32 m0, s57
	s_nop 0
	global_load_lds_dwordx4 v132, s[44:45]
	s_waitcnt vmcnt(8)
	s_waitcnt lgkmcnt(0)
	s_barrier
	s_waitcnt lgkmcnt(0)
	v_mfma_f32_16x16x32_bf16 v[126:129], v[148:151], v[196:199], v[126:129]
	v_mfma_f32_16x16x32_bf16 v[122:125], v[156:159], v[196:199], v[122:125]
	v_mfma_f32_16x16x32_bf16 v[110:113], v[148:151], v[204:207], v[110:113]
	v_mfma_f32_16x16x32_bf16 v[106:109], v[156:159], v[204:207], v[106:109]
	v_mfma_f32_16x16x32_bf16 v[94:97], v[148:151], v[212:215], v[94:97]
	v_mfma_f32_16x16x32_bf16 v[90:93], v[156:159], v[212:215], v[90:93]
	v_mfma_f32_16x16x32_bf16 v[78:81], v[148:151], v[224:227], v[78:81]
	v_mfma_f32_16x16x32_bf16 v[74:77], v[156:159], v[224:227], v[74:77]
	v_mfma_f32_16x16x32_bf16 v[126:129], v[152:155], v[200:203], v[126:129]
	v_mfma_f32_16x16x32_bf16 v[122:125], v[160:163], v[200:203], v[122:125]
	v_mfma_f32_16x16x32_bf16 v[110:113], v[152:155], v[208:211], v[110:113]
	v_mfma_f32_16x16x32_bf16 v[106:109], v[160:163], v[208:211], v[106:109]
	v_mfma_f32_16x16x32_bf16 v[94:97], v[152:155], v[216:219], v[94:97]
	v_mfma_f32_16x16x32_bf16 v[90:93], v[160:163], v[216:219], v[90:93]
	v_mfma_f32_16x16x32_bf16 v[78:81], v[152:155], v[228:231], v[78:81]
	v_mfma_f32_16x16x32_bf16 v[74:77], v[160:163], v[228:231], v[74:77]
	v_mfma_f32_16x16x32_bf16 v[118:121], v[180:183], v[196:199], v[118:121]
	v_mfma_f32_16x16x32_bf16 v[114:117], v[188:191], v[196:199], v[114:117]
	v_mfma_f32_16x16x32_bf16 v[102:105], v[180:183], v[204:207], v[102:105]
	v_mfma_f32_16x16x32_bf16 v[98:101], v[188:191], v[204:207], v[98:101]
	v_mfma_f32_16x16x32_bf16 v[86:89], v[180:183], v[212:215], v[86:89]
	v_mfma_f32_16x16x32_bf16 v[82:85], v[188:191], v[212:215], v[82:85]
	v_mfma_f32_16x16x32_bf16 v[70:73], v[180:183], v[224:227], v[70:73]
	v_mfma_f32_16x16x32_bf16 v[66:69], v[188:191], v[224:227], v[66:69]
	v_mfma_f32_16x16x32_bf16 v[118:121], v[184:187], v[200:203], v[118:121]
	v_mfma_f32_16x16x32_bf16 v[114:117], v[192:195], v[200:203], v[114:117]
	v_mfma_f32_16x16x32_bf16 v[102:105], v[184:187], v[208:211], v[102:105]
	v_mfma_f32_16x16x32_bf16 v[98:101], v[192:195], v[208:211], v[98:101]
	v_mfma_f32_16x16x32_bf16 v[86:89], v[184:187], v[216:219], v[86:89]
	v_mfma_f32_16x16x32_bf16 v[82:85], v[192:195], v[216:219], v[82:85]
	v_mfma_f32_16x16x32_bf16 v[70:73], v[184:187], v[228:231], v[70:73]
	v_mfma_f32_16x16x32_bf16 v[66:69], v[192:195], v[228:231], v[66:69]
	s_barrier
; #define PG8_STAGE(bufoff, gbase, voff) do { _Pragma("unroll") for (int _i = 0; _i < 2; ++_i) \
;         __builtin_amdgcn_global_load_lds((const unsigned*)((const char*)(gbase) + (voff)[_i]), (PG8_LAS unsigned*)(lds + (bufoff) + ldsw + _i * 8192), 16, 0, 0); } while (0)
; #define PG8_LDA(dst, b, h) do { _Pragma("unroll") for (int m = 0; m < 4; ++m) _Pragma("unroll") for (int k = 0; k < 2; ++k) dst[m][k] = *(const PG8_LAS bf16x8*)(lds + PG8_SA(b, h) + aoff + m * 2048 + k * 1024); } while (0)
; #define PG8_MMA(ai, bj, At, Bt) do { __builtin_amdgcn_s_setprio(1); _Pragma("unroll") for (int m = 0; m < 4; ++m) _Pragma("unroll") for (int n = 0; n < 2; ++n) _Pragma("unroll") for (int k = 0; k < 2; ++k) \
;         acc[ai][bj][m][n] = __builtin_amdgcn_mfma_f32_16x16x32_bf16(Bt[n][k], At[m][k], acc[ai][bj][m][n], 0, 0, 0); __builtin_amdgcn_s_setprio(0); } while (0)
; #define PG8_WAIT_V(n) asm volatile("s_waitcnt vmcnt(" #n ")" ::: "memory")
; #define PG8_WAIT_L(n) asm volatile("s_waitcnt lgkmcnt(" #n ")" ::: "memory")
; #define PG8_BAR __builtin_amdgcn_s_barrier()
; #define PG8_SCHED __builtin_amdgcn_sched_barrier(0)
; template <class Epi, class Sched, bool ALIGN_EPI = false, bool SP2 = false>
; __device__ __forceinline__ void gemm_phase(PG8_LAS unsigned char* lds, const Gemm g, const Sched& S, const Epi& E) {
;     ...
;             PG8_LDA(At, 1, 1); PG8_STAGE(PG8_SB(1, 0), b3, voffB); PG8_STAGE(PG8_SB(1, 1), b3 + hB, voffB); PG8_STAGE(PG8_SA(1, 0), a3, voffA);
;             PG8_WAIT_V(8); PG8_WAIT_L(0); PG8_BAR; PG8_MMA(1, 0, At, B0); PG8_MMA(1, 1, At, B1); PG8_BAR; PG8_SCHED;
	s_add_i32 s18, s18, s49
	s_mov_b32 m0, s18
	ds_read_b128 v[196:199], v173 offset:49152
	ds_read_b128 v[200:203], v173 offset:50176
	ds_read_b128 v[204:207], v173 offset:51200
	ds_read_b128 v[208:211], v173 offset:52224
	ds_read_b128 v[212:215], v173 offset:53248
	ds_read_b128 v[216:219], v173 offset:54272
	ds_read_b128 v[224:227], v173 offset:55296
	ds_read_b128 v[228:231], v173 offset:56320
	global_load_lds_dwordx4 v134, s[76:77]
	s_add_i32 m0, s18, 0x2000
	s_add_u32 s42, s42, 0x80080
	s_addc_u32 s43, s43, 0
	s_add_i32 s18, s19, s49
	global_load_lds_dwordx4 v130, s[76:77]
	s_mov_b32 m0, s18
	s_nop 0
	global_load_lds_dwordx4 v134, s[42:43]
	s_add_i32 m0, s18, 0x2000
	s_nop 0
	global_load_lds_dwordx4 v130, s[42:43]
	s_mov_b32 m0, s60
	s_nop 0
	global_load_lds_dwordx4 v136, s[78:79]
	s_mov_b32 m0, s61
	s_nop 0
	global_load_lds_dwordx4 v132, s[78:79]
	s_waitcnt vmcnt(8)
	s_waitcnt lgkmcnt(0)
	s_barrier
	s_waitcnt lgkmcnt(0)
	v_mfma_f32_16x16x32_bf16 v[62:65], v[148:151], v[196:199], v[62:65]
	v_mfma_f32_16x16x32_bf16 v[58:61], v[156:159], v[196:199], v[58:61]
	v_mfma_f32_16x16x32_bf16 v[46:49], v[148:151], v[204:207], v[46:49]
	v_mfma_f32_16x16x32_bf16 v[42:45], v[156:159], v[204:207], v[42:45]
	v_mfma_f32_16x16x32_bf16 v[30:33], v[148:151], v[212:215], v[30:33]
	v_mfma_f32_16x16x32_bf16 v[26:29], v[156:159], v[212:215], v[26:29]
	v_mfma_f32_16x16x32_bf16 v[14:17], v[148:151], v[224:227], v[14:17]
	v_mfma_f32_16x16x32_bf16 v[10:13], v[156:159], v[224:227], v[10:13]
	v_mfma_f32_16x16x32_bf16 v[62:65], v[152:155], v[200:203], v[62:65]
	v_mfma_f32_16x16x32_bf16 v[58:61], v[160:163], v[200:203], v[58:61]
	v_mfma_f32_16x16x32_bf16 v[46:49], v[152:155], v[208:211], v[46:49]
	v_mfma_f32_16x16x32_bf16 v[42:45], v[160:163], v[208:211], v[42:45]
	v_mfma_f32_16x16x32_bf16 v[30:33], v[152:155], v[216:219], v[30:33]
	v_mfma_f32_16x16x32_bf16 v[26:29], v[160:163], v[216:219], v[26:29]
	v_mfma_f32_16x16x32_bf16 v[14:17], v[152:155], v[228:231], v[14:17]
	v_mfma_f32_16x16x32_bf16 v[10:13], v[160:163], v[228:231], v[10:13]
	v_mfma_f32_16x16x32_bf16 v[54:57], v[180:183], v[196:199], v[54:57]
	v_mfma_f32_16x16x32_bf16 v[50:53], v[188:191], v[196:199], v[50:53]
	v_mfma_f32_16x16x32_bf16 v[38:41], v[180:183], v[204:207], v[38:41]
	v_mfma_f32_16x16x32_bf16 v[34:37], v[188:191], v[204:207], v[34:37]
	v_mfma_f32_16x16x32_bf16 v[22:25], v[180:183], v[212:215], v[22:25]
	v_mfma_f32_16x16x32_bf16 v[18:21], v[188:191], v[212:215], v[18:21]
	v_mfma_f32_16x16x32_bf16 v[6:9], v[180:183], v[224:227], v[6:9]
	v_mfma_f32_16x16x32_bf16 v[2:5], v[188:191], v[224:227], v[2:5]
	v_mfma_f32_16x16x32_bf16 v[54:57], v[184:187], v[200:203], v[54:57]
	v_mfma_f32_16x16x32_bf16 v[50:53], v[192:195], v[200:203], v[50:53]
	v_mfma_f32_16x16x32_bf16 v[38:41], v[184:187], v[208:211], v[38:41]
	v_mfma_f32_16x16x32_bf16 v[34:37], v[192:195], v[208:211], v[34:37]
	v_mfma_f32_16x16x32_bf16 v[22:25], v[184:187], v[216:219], v[22:25]
	v_mfma_f32_16x16x32_bf16 v[18:21], v[192:195], v[216:219], v[18:21]
	v_mfma_f32_16x16x32_bf16 v[6:9], v[184:187], v[228:231], v[6:9]
	v_mfma_f32_16x16x32_bf16 v[2:5], v[192:195], v[228:231], v[2:5]
	s_barrier
	s_add_i32 s72, s72, 2
	s_add_u32 s8, s8, 0x100
	s_addc_u32 s9, s9, 0
	s_add_u32 s70, s70, 0x100
	s_addc_u32 s71, s71, 0
	s_cmp_gt_u32 s72, 29

; #define PG8_STAGE(bufoff, gbase, voff) do { _Pragma("unroll") for (int _i = 0; _i < 2; ++_i) \
;         __builtin_amdgcn_global_load_lds((const unsigned*)((const char*)(gbase) + (voff)[_i]), (PG8_LAS unsigned*)(lds + (bufoff) + ldsw + _i * 8192), 16, 0, 0); } while (0)
; #define PG8_LDA(dst, b, h) do { _Pragma("unroll") for (int m = 0; m < 4; ++m) _Pragma("unroll") for (int k = 0; k < 2; ++k) dst[m][k] = *(const PG8_LAS bf16x8*)(lds + PG8_SA(b, h) + aoff + m * 2048 + k * 1024); } while (0)
; #define PG8_LDB(dst, b, h) do { _Pragma("unroll") for (int n = 0; n < 2; ++n) _Pragma("unroll") for (int k = 0; k < 2; ++k) dst[n][k] = *(const PG8_LAS bf16x8*)(lds + PG8_SB(b, h) + boff + n * 2048 + k * 1024); } while (0)
; #define PG8_MMA(ai, bj, At, Bt) do { __builtin_amdgcn_s_setprio(1); _Pragma("unroll") for (int m = 0; m < 4; ++m) _Pragma("unroll") for (int n = 0; n < 2; ++n) _Pragma("unroll") for (int k = 0; k < 2; ++k) \
;         acc[ai][bj][m][n] = __builtin_amdgcn_mfma_f32_16x16x32_bf16(Bt[n][k], At[m][k], acc[ai][bj][m][n], 0, 0, 0); __builtin_amdgcn_s_setprio(0); } while (0)
; #define PG8_WAIT_V(n) asm volatile("s_waitcnt vmcnt(" #n ")" ::: "memory")
; #define PG8_WAIT_L(n) asm volatile("s_waitcnt lgkmcnt(" #n ")" ::: "memory")
; #define PG8_BAR __builtin_amdgcn_s_barrier()
; #define PG8_SCHED __builtin_amdgcn_sched_barrier(0)
; template <class Epi, class Sched, bool ALIGN_EPI = false, bool SP2 = false>
; __device__ __forceinline__ void gemm_phase(PG8_LAS unsigned char* lds, const Gemm g, const Sched& S, const Epi& E) {
;     ...
;             PG8_LDB(B0, 0, 0); PG8_LDB(B1, 0, 1); PG8_SCHED; PG8_LDA(At, 0, 0); PG8_STAGE(PG8_SA(1, 1), a1 + hA, voffA);
;             PG8_WAIT_V(8); PG8_WAIT_L(0); PG8_BAR; PG8_MMA(0, 0, At, B0); PG8_MMA(0, 1, At, B1); PG8_BAR; PG8_SCHED;
;             PG8_LDA(At, 0, 1); PG8_STAGE(PG8_SB(0, 0), b2, voffB); PG8_STAGE(PG8_SB(0, 1), b2 + hB, voffB); PG8_STAGE(PG8_SA(0, 0), a2, voffA);
;             PG8_WAIT_V(8); PG8_WAIT_L(0); PG8_BAR; PG8_MMA(1, 0, At, B0); PG8_MMA(1, 1, At, B1); PG8_BAR; PG8_SCHED;
.LBB0_1126:
	s_add_u32 s61, s36, 0x100
	v_mov_b32_e32 v2, 0
	s_addc_u32 s62, s37, 0
	s_mov_b32 s63, -2
	s_waitcnt lgkmcnt(0)
	v_mov_b32_e32 v3, v2
	ds_read_b128 v[130:133], v190
	ds_read_b128 v[134:137], v190 offset:1024
	ds_read_b128 v[138:141], v190 offset:2048
	ds_read_b128 v[142:145], v190 offset:3072
	ds_read_b128 v[146:149], v191
	ds_read_b128 v[150:153], v191 offset:1024
	ds_read_b128 v[170:173], v191 offset:2048
	ds_read_b128 v[174:177], v191 offset:3072
	s_add_u32 s36, s24, 0x100
	s_addc_u32 s37, s25, 0
	s_cmpk_eq_i32 s63, 0x54
	s_cselect_b32 s41, s9, s37
	s_cselect_b32 s40, s8, s36
	s_cselect_b32 s39, s23, s62
	s_cselect_b32 s38, s22, s61
	s_add_i32 m0, s46, 0xc000
	ds_read_b128 v[178:181], v192
	ds_read_b128 v[182:185], v192 offset:1024
	ds_read_b128 v[194:197], v192 offset:2048
	ds_read_b128 v[198:201], v192 offset:3072
	ds_read_b128 v[202:205], v192 offset:4096
	ds_read_b128 v[206:209], v192 offset:5120
	ds_read_b128 v[210:213], v192 offset:6144
	ds_read_b128 v[214:217], v192 offset:7168
	global_load_lds_dwordx4 v162, s[24:25]
	s_add_i32 m0, s46, 0xe000
	s_nop 0
	global_load_lds_dwordx4 v164, s[24:25]
	s_waitcnt vmcnt(8)
	s_waitcnt lgkmcnt(0)
	s_barrier
	s_waitcnt lgkmcnt(0)
	v_mfma_f32_16x16x32_bf16 v[126:129], v[130:133], v[178:181], 0
	v_mfma_f32_16x16x32_bf16 v[122:125], v[138:141], v[178:181], 0
	v_mfma_f32_16x16x32_bf16 v[110:113], v[130:133], v[194:197], 0
	v_mfma_f32_16x16x32_bf16 v[106:109], v[138:141], v[194:197], 0
	v_mfma_f32_16x16x32_bf16 v[94:97], v[130:133], v[202:205], 0
	v_mfma_f32_16x16x32_bf16 v[90:93], v[138:141], v[202:205], 0
	v_mfma_f32_16x16x32_bf16 v[78:81], v[130:133], v[210:213], 0
	v_mfma_f32_16x16x32_bf16 v[74:77], v[138:141], v[210:213], 0
	v_mfma_f32_16x16x32_bf16 v[126:129], v[134:137], v[182:185], v[126:129]
	v_mfma_f32_16x16x32_bf16 v[122:125], v[142:145], v[182:185], v[122:125]
	v_mfma_f32_16x16x32_bf16 v[110:113], v[134:137], v[198:201], v[110:113]
	v_mfma_f32_16x16x32_bf16 v[106:109], v[142:145], v[198:201], v[106:109]
	v_mfma_f32_16x16x32_bf16 v[94:97], v[134:137], v[206:209], v[94:97]
	v_mfma_f32_16x16x32_bf16 v[90:93], v[142:145], v[206:209], v[90:93]
	v_mfma_f32_16x16x32_bf16 v[78:81], v[134:137], v[214:217], v[78:81]
	v_mfma_f32_16x16x32_bf16 v[74:77], v[142:145], v[214:217], v[74:77]
	v_mfma_f32_16x16x32_bf16 v[118:121], v[146:149], v[178:181], 0
	v_mfma_f32_16x16x32_bf16 v[114:117], v[170:173], v[178:181], 0
	v_mfma_f32_16x16x32_bf16 v[102:105], v[146:149], v[194:197], 0
	v_mfma_f32_16x16x32_bf16 v[98:101], v[170:173], v[194:197], 0
	v_mfma_f32_16x16x32_bf16 v[86:89], v[146:149], v[202:205], 0
	v_mfma_f32_16x16x32_bf16 v[82:85], v[170:173], v[202:205], 0
	v_mfma_f32_16x16x32_bf16 v[70:73], v[146:149], v[210:213], 0
	v_mfma_f32_16x16x32_bf16 v[66:69], v[170:173], v[210:213], 0
	v_mfma_f32_16x16x32_bf16 v[118:121], v[150:153], v[182:185], v[118:121]
	v_mfma_f32_16x16x32_bf16 v[114:117], v[174:177], v[182:185], v[114:117]
	v_mfma_f32_16x16x32_bf16 v[102:105], v[150:153], v[198:201], v[102:105]
	v_mfma_f32_16x16x32_bf16 v[98:101], v[174:177], v[198:201], v[98:101]
	v_mfma_f32_16x16x32_bf16 v[86:89], v[150:153], v[206:209], v[86:89]
	v_mfma_f32_16x16x32_bf16 v[82:85], v[174:177], v[206:209], v[82:85]
	v_mfma_f32_16x16x32_bf16 v[70:73], v[150:153], v[214:217], v[70:73]
	v_mfma_f32_16x16x32_bf16 v[66:69], v[174:177], v[214:217], v[66:69]
	s_barrier
	s_add_i32 s18, s55, s45
	s_add_u32 s76, s38, s16
	s_addc_u32 s77, s39, s17
	s_mov_b32 m0, s18
	ds_read_b128 v[178:181], v192 offset:16384
	ds_read_b128 v[182:185], v192 offset:17408
	ds_read_b128 v[194:197], v192 offset:18432
	ds_read_b128 v[198:201], v192 offset:19456
	ds_read_b128 v[202:205], v192 offset:20480
	ds_read_b128 v[206:209], v192 offset:21504
	ds_read_b128 v[210:213], v192 offset:22528
	ds_read_b128 v[214:217], v192 offset:23552
	global_load_lds_dwordx4 v156, s[38:39]
	s_add_i32 m0, s18, 0x2000
	s_add_u32 s24, s38, 0x160000
	s_addc_u32 s25, s39, 0
	s_add_i32 s18, s56, s45
	global_load_lds_dwordx4 v160, s[38:39]
	s_mov_b32 m0, s18
	s_nop 0
	global_load_lds_dwordx4 v156, s[24:25]
	s_add_i32 m0, s18, 0x2000
	s_nop 0
	global_load_lds_dwordx4 v160, s[24:25]
	s_add_u32 s78, s40, s16
	s_addc_u32 s79, s41, s17
	s_mov_b32 m0, s46
	s_nop 0
	global_load_lds_dwordx4 v154, s[40:41]
	s_mov_b32 m0, s47
	s_nop 0
	global_load_lds_dwordx4 v158, s[40:41]
	s_waitcnt vmcnt(8)
	s_waitcnt lgkmcnt(0)
	s_barrier
	s_waitcnt lgkmcnt(0)
	v_mfma_f32_16x16x32_bf16 v[62:65], v[130:133], v[178:181], 0
	v_mfma_f32_16x16x32_bf16 v[58:61], v[138:141], v[178:181], 0
	v_mfma_f32_16x16x32_bf16 v[46:49], v[130:133], v[194:197], 0
	v_mfma_f32_16x16x32_bf16 v[42:45], v[138:141], v[194:197], 0
	v_mfma_f32_16x16x32_bf16 v[30:33], v[130:133], v[202:205], 0
	v_mfma_f32_16x16x32_bf16 v[26:29], v[138:141], v[202:205], 0
	v_mfma_f32_16x16x32_bf16 v[14:17], v[130:133], v[210:213], 0
	v_mfma_f32_16x16x32_bf16 v[10:13], v[138:141], v[210:213], 0
	v_mfma_f32_16x16x32_bf16 v[62:65], v[134:137], v[182:185], v[62:65]
	v_mfma_f32_16x16x32_bf16 v[58:61], v[142:145], v[182:185], v[58:61]
	v_mfma_f32_16x16x32_bf16 v[46:49], v[134:137], v[198:201], v[46:49]
	v_mfma_f32_16x16x32_bf16 v[42:45], v[142:145], v[198:201], v[42:45]
	v_mfma_f32_16x16x32_bf16 v[30:33], v[134:137], v[206:209], v[30:33]
	v_mfma_f32_16x16x32_bf16 v[26:29], v[142:145], v[206:209], v[26:29]
	v_mfma_f32_16x16x32_bf16 v[14:17], v[134:137], v[214:217], v[14:17]
	v_mfma_f32_16x16x32_bf16 v[10:13], v[142:145], v[214:217], v[10:13]
	v_mfma_f32_16x16x32_bf16 v[54:57], v[146:149], v[178:181], 0
	v_mfma_f32_16x16x32_bf16 v[50:53], v[170:173], v[178:181], 0
	v_mfma_f32_16x16x32_bf16 v[38:41], v[146:149], v[194:197], 0
	v_mfma_f32_16x16x32_bf16 v[34:37], v[170:173], v[194:197], 0
	v_mfma_f32_16x16x32_bf16 v[22:25], v[146:149], v[202:205], 0
	v_mfma_f32_16x16x32_bf16 v[18:21], v[170:173], v[202:205], 0
	v_mfma_f32_16x16x32_bf16 v[6:9], v[146:149], v[210:213], 0
	v_mfma_f32_16x16x32_bf16 v[2:5], v[170:173], v[210:213], 0
	v_mfma_f32_16x16x32_bf16 v[54:57], v[150:153], v[182:185], v[54:57]
	v_mfma_f32_16x16x32_bf16 v[50:53], v[174:177], v[182:185], v[50:53]
	v_mfma_f32_16x16x32_bf16 v[38:41], v[150:153], v[198:201], v[38:41]
	v_mfma_f32_16x16x32_bf16 v[34:37], v[174:177], v[198:201], v[34:37]
	v_mfma_f32_16x16x32_bf16 v[22:25], v[150:153], v[206:209], v[22:25]
	v_mfma_f32_16x16x32_bf16 v[18:21], v[174:177], v[206:209], v[18:21]
	v_mfma_f32_16x16x32_bf16 v[6:9], v[150:153], v[214:217], v[6:9]
	v_mfma_f32_16x16x32_bf16 v[2:5], v[174:177], v[214:217], v[2:5]
	s_barrier
; #define PG8_STAGE(bufoff, gbase, voff) do { _Pragma("unroll") for (int _i = 0; _i < 2; ++_i) \
;         __builtin_amdgcn_global_load_lds((const unsigned*)((const char*)(gbase) + (voff)[_i]), (PG8_LAS unsigned*)(lds + (bufoff) + ldsw + _i * 8192), 16, 0, 0); } while (0)
; #define PG8_LDA(dst, b, h) do { _Pragma("unroll") for (int m = 0; m < 4; ++m) _Pragma("unroll") for (int k = 0; k < 2; ++k) dst[m][k] = *(const PG8_LAS bf16x8*)(lds + PG8_SA(b, h) + aoff + m * 2048 + k * 1024); } while (0)
; #define PG8_LDB(dst, b, h) do { _Pragma("unroll") for (int n = 0; n < 2; ++n) _Pragma("unroll") for (int k = 0; k < 2; ++k) dst[n][k] = *(const PG8_LAS bf16x8*)(lds + PG8_SB(b, h) + boff + n * 2048 + k * 1024); } while (0)
; #define PG8_MMA(ai, bj, At, Bt) do { __builtin_amdgcn_s_setprio(1); _Pragma("unroll") for (int m = 0; m < 4; ++m) _Pragma("unroll") for (int n = 0; n < 2; ++n) _Pragma("unroll") for (int k = 0; k < 2; ++k) \
;         acc[ai][bj][m][n] = __builtin_amdgcn_mfma_f32_16x16x32_bf16(Bt[n][k], At[m][k], acc[ai][bj][m][n], 0, 0, 0); __builtin_amdgcn_s_setprio(0); } while (0)
; #define PG8_WAIT_V(n) asm volatile("s_waitcnt vmcnt(" #n ")" ::: "memory")
; #define PG8_WAIT_L(n) asm volatile("s_waitcnt lgkmcnt(" #n ")" ::: "memory")
; #define PG8_BAR __builtin_amdgcn_s_barrier()
; #define PG8_SCHED __builtin_amdgcn_sched_barrier(0)
; template <class Epi, class Sched, bool ALIGN_EPI = false, bool SP2 = false>
; __device__ __forceinline__ void gemm_phase(PG8_LAS unsigned char* lds, const Gemm g, const Sched& S, const Epi& E) {
;     ...
;             PG8_LDB(B0, 1, 0); PG8_LDB(B1, 1, 1); PG8_SCHED; PG8_LDA(At, 1, 0); PG8_STAGE(PG8_SA(0, 1), a2 + hA, voffA);
;             PG8_WAIT_V(8); PG8_WAIT_L(0); PG8_BAR; PG8_MMA(0, 0, At, B0); PG8_MMA(0, 1, At, B1); PG8_BAR; PG8_SCHED;
;             PG8_LDA(At, 1, 1); PG8_STAGE(PG8_SB(1, 0), b3, voffB); PG8_STAGE(PG8_SB(1, 1), b3 + hB, voffB); PG8_STAGE(PG8_SA(1, 0), a3, voffA);
;             PG8_WAIT_V(8); PG8_WAIT_L(0); PG8_BAR; PG8_MMA(1, 0, At, B0); PG8_MMA(1, 1, At, B1); PG8_BAR; PG8_SCHED;
	s_add_i32 s18, 0, 0x18000
	s_add_i32 s19, 0, 0x1c000
	v_add_u32_e32 v142, s18, v188
	v_add_u32_e32 v174, s19, v188
	ds_read_b128 v[130:133], v142
	ds_read_b128 v[134:137], v142 offset:1024
	ds_read_b128 v[138:141], v142 offset:2048
	ds_read_b128 v[142:145], v142 offset:3072
	ds_read_b128 v[146:149], v174
	ds_read_b128 v[150:153], v174 offset:1024
	ds_read_b128 v[170:173], v174 offset:2048
	ds_read_b128 v[174:177], v174 offset:3072
	s_add_u32 s24, s40, 0x160000
	s_addc_u32 s25, s41, 0
	s_mov_b32 m0, s48
	ds_read_b128 v[178:181], v192 offset:32768
	ds_read_b128 v[182:185], v192 offset:33792
	ds_read_b128 v[194:197], v192 offset:34816
	ds_read_b128 v[198:201], v192 offset:35840
	ds_read_b128 v[202:205], v192 offset:36864
	ds_read_b128 v[206:209], v192 offset:37888
	ds_read_b128 v[210:213], v192 offset:38912
	ds_read_b128 v[214:217], v192 offset:39936
	global_load_lds_dwordx4 v154, s[24:25]
	s_mov_b32 m0, s49
	s_nop 0
	global_load_lds_dwordx4 v158, s[24:25]
	s_waitcnt vmcnt(8)
	s_waitcnt lgkmcnt(0)
	s_barrier
	s_waitcnt lgkmcnt(0)
	v_mfma_f32_16x16x32_bf16 v[126:129], v[130:133], v[178:181], v[126:129]
	v_mfma_f32_16x16x32_bf16 v[122:125], v[138:141], v[178:181], v[122:125]
	v_mfma_f32_16x16x32_bf16 v[110:113], v[130:133], v[194:197], v[110:113]
	v_mfma_f32_16x16x32_bf16 v[106:109], v[138:141], v[194:197], v[106:109]
	v_mfma_f32_16x16x32_bf16 v[94:97], v[130:133], v[202:205], v[94:97]
	v_mfma_f32_16x16x32_bf16 v[90:93], v[138:141], v[202:205], v[90:93]
	v_mfma_f32_16x16x32_bf16 v[78:81], v[130:133], v[210:213], v[78:81]
	v_mfma_f32_16x16x32_bf16 v[74:77], v[138:141], v[210:213], v[74:77]
	v_mfma_f32_16x16x32_bf16 v[126:129], v[134:137], v[182:185], v[126:129]
	v_mfma_f32_16x16x32_bf16 v[122:125], v[142:145], v[182:185], v[122:125]
	v_mfma_f32_16x16x32_bf16 v[110:113], v[134:137], v[198:201], v[110:113]
	v_mfma_f32_16x16x32_bf16 v[106:109], v[142:145], v[198:201], v[106:109]
	v_mfma_f32_16x16x32_bf16 v[94:97], v[134:137], v[206:209], v[94:97]
	v_mfma_f32_16x16x32_bf16 v[90:93], v[142:145], v[206:209], v[90:93]
	v_mfma_f32_16x16x32_bf16 v[78:81], v[134:137], v[214:217], v[78:81]
	v_mfma_f32_16x16x32_bf16 v[74:77], v[142:145], v[214:217], v[74:77]
	v_mfma_f32_16x16x32_bf16 v[118:121], v[146:149], v[178:181], v[118:121]
	v_mfma_f32_16x16x32_bf16 v[114:117], v[170:173], v[178:181], v[114:117]
	v_mfma_f32_16x16x32_bf16 v[102:105], v[146:149], v[194:197], v[102:105]
	v_mfma_f32_16x16x32_bf16 v[98:101], v[170:173], v[194:197], v[98:101]
	v_mfma_f32_16x16x32_bf16 v[86:89], v[146:149], v[202:205], v[86:89]
	v_mfma_f32_16x16x32_bf16 v[82:85], v[170:173], v[202:205], v[82:85]
	v_mfma_f32_16x16x32_bf16 v[70:73], v[146:149], v[210:213], v[70:73]
	v_mfma_f32_16x16x32_bf16 v[66:69], v[170:173], v[210:213], v[66:69]
	v_mfma_f32_16x16x32_bf16 v[118:121], v[150:153], v[182:185], v[118:121]
	v_mfma_f32_16x16x32_bf16 v[114:117], v[174:177], v[182:185], v[114:117]
	v_mfma_f32_16x16x32_bf16 v[102:105], v[150:153], v[198:201], v[102:105]
	v_mfma_f32_16x16x32_bf16 v[98:101], v[174:177], v[198:201], v[98:101]
	v_mfma_f32_16x16x32_bf16 v[86:89], v[150:153], v[206:209], v[86:89]
	v_mfma_f32_16x16x32_bf16 v[82:85], v[174:177], v[206:209], v[82:85]
	v_mfma_f32_16x16x32_bf16 v[70:73], v[150:153], v[214:217], v[70:73]
	v_mfma_f32_16x16x32_bf16 v[66:69], v[174:177], v[214:217], v[66:69]
	s_barrier
	s_add_i32 s18, s18, s45
	s_mov_b32 m0, s18
	ds_read_b128 v[178:181], v192 offset:49152
	ds_read_b128 v[182:185], v192 offset:50176
	ds_read_b128 v[194:197], v192 offset:51200
	ds_read_b128 v[198:201], v192 offset:52224
	ds_read_b128 v[202:205], v192 offset:53248
	ds_read_b128 v[206:209], v192 offset:54272
	ds_read_b128 v[210:213], v192 offset:55296
	ds_read_b128 v[214:217], v192 offset:56320
	global_load_lds_dwordx4 v156, s[76:77]
	s_add_i32 m0, s18, 0x2000
	s_add_u32 s24, s38, 0x160080
	s_addc_u32 s25, s39, 0
	s_add_i32 s18, s19, s45
	global_load_lds_dwordx4 v160, s[76:77]
	s_mov_b32 m0, s18
	s_nop 0
	global_load_lds_dwordx4 v156, s[24:25]
	s_add_i32 m0, s18, 0x2000
	s_nop 0
	global_load_lds_dwordx4 v160, s[24:25]
	s_mov_b32 m0, s52
	s_nop 0
	global_load_lds_dwordx4 v154, s[78:79]
	s_mov_b32 m0, s53
	s_nop 0
	global_load_lds_dwordx4 v158, s[78:79]
	s_waitcnt vmcnt(8)
	s_waitcnt lgkmcnt(0)
	s_barrier
	s_waitcnt lgkmcnt(0)
	v_mfma_f32_16x16x32_bf16 v[62:65], v[130:133], v[178:181], v[62:65]
	v_mfma_f32_16x16x32_bf16 v[58:61], v[138:141], v[178:181], v[58:61]
	v_mfma_f32_16x16x32_bf16 v[46:49], v[130:133], v[194:197], v[46:49]
	v_mfma_f32_16x16x32_bf16 v[42:45], v[138:141], v[194:197], v[42:45]
	v_mfma_f32_16x16x32_bf16 v[30:33], v[130:133], v[202:205], v[30:33]
	v_mfma_f32_16x16x32_bf16 v[26:29], v[138:141], v[202:205], v[26:29]
	v_mfma_f32_16x16x32_bf16 v[14:17], v[130:133], v[210:213], v[14:17]
	v_mfma_f32_16x16x32_bf16 v[10:13], v[138:141], v[210:213], v[10:13]
	v_mfma_f32_16x16x32_bf16 v[62:65], v[134:137], v[182:185], v[62:65]
	v_mfma_f32_16x16x32_bf16 v[58:61], v[142:145], v[182:185], v[58:61]
	v_mfma_f32_16x16x32_bf16 v[46:49], v[134:137], v[198:201], v[46:49]
	v_mfma_f32_16x16x32_bf16 v[42:45], v[142:145], v[198:201], v[42:45]
	v_mfma_f32_16x16x32_bf16 v[30:33], v[134:137], v[206:209], v[30:33]
	v_mfma_f32_16x16x32_bf16 v[26:29], v[142:145], v[206:209], v[26:29]
	v_mfma_f32_16x16x32_bf16 v[14:17], v[134:137], v[214:217], v[14:17]
	v_mfma_f32_16x16x32_bf16 v[10:13], v[142:145], v[214:217], v[10:13]
	v_mfma_f32_16x16x32_bf16 v[54:57], v[146:149], v[178:181], v[54:57]
	v_mfma_f32_16x16x32_bf16 v[50:53], v[170:173], v[178:181], v[50:53]
	v_mfma_f32_16x16x32_bf16 v[38:41], v[146:149], v[194:197], v[38:41]
	v_mfma_f32_16x16x32_bf16 v[34:37], v[170:173], v[194:197], v[34:37]
	v_mfma_f32_16x16x32_bf16 v[22:25], v[146:149], v[202:205], v[22:25]
	v_mfma_f32_16x16x32_bf16 v[18:21], v[170:173], v[202:205], v[18:21]
	v_mfma_f32_16x16x32_bf16 v[6:9], v[146:149], v[210:213], v[6:9]
	v_mfma_f32_16x16x32_bf16 v[2:5], v[170:173], v[210:213], v[2:5]
	v_mfma_f32_16x16x32_bf16 v[54:57], v[150:153], v[182:185], v[54:57]
	v_mfma_f32_16x16x32_bf16 v[50:53], v[174:177], v[182:185], v[50:53]
	v_mfma_f32_16x16x32_bf16 v[38:41], v[150:153], v[198:201], v[38:41]
	v_mfma_f32_16x16x32_bf16 v[34:37], v[174:177], v[198:201], v[34:37]
	v_mfma_f32_16x16x32_bf16 v[22:25], v[150:153], v[206:209], v[22:25]
	v_mfma_f32_16x16x32_bf16 v[18:21], v[174:177], v[206:209], v[18:21]
	v_mfma_f32_16x16x32_bf16 v[6:9], v[150:153], v[214:217], v[6:9]
	v_mfma_f32_16x16x32_bf16 v[2:5], v[174:177], v[214:217], v[2:5]
	s_barrier
	s_add_i32 s63, s63, 2
	s_add_u32 s61, s61, 0x100
	s_addc_u32 s62, s62, 0
	s_cmpk_gt_u32 s63, 0x55
	s_mov_b64 s[24:25], s[36:37]
